# in-proj epilogue for proj tiles hand-written: rstd prefetched in tile prologue, scale/silu/pack, LDS-transposed dwordx4 full-row stores
# speedup vs baseline: 1.0541x; 1.0156x over previous
.LBB0_142:
	s_mul_hi_i32 s0, s54, 0x2aaaaaab
	s_lshr_b32 s1, s0, 31
	s_ashr_i32 s6, s0, 2
	s_add_i32 s6, s6, s1
	s_mul_i32 s0, s6, 24
	v_readlane_b32 s4, v230, 1
	s_sub_i32 s8, s54, s0
	s_lshl_b32 s0, s6, 20
	v_readlane_b32 s5, v230, 2
	s_add_i32 s1, s4, s0
	v_readlane_b32 s4, v229, 47
	v_mov_b32_e32 v2, v194
	v_readlane_b32 s60, v230, 18
	s_lshl_b32 s2, s8, 20
	s_mul_i32 s4, s4, 0x1800000
	v_readlane_b32 s70, v230, 28
	v_ashrrev_i32_e32 v3, 6, v2
	v_bfe_u32 v4, v2, 3, 3
	v_readlane_b32 s5, v229, 48
	s_add_i32 s4, s2, s4
	v_and_b32_e32 v204, 3, v3
	v_lshlrev_b32_e32 v7, 2, v3
	v_lshlrev_b32_e32 v208, 12, v3
	v_lshlrev_b32_e32 v8, 4, v2
	v_and_b32_e32 v9, 48, v2
	s_movk_i32 s2, 0x70
	v_lshlrev_b32_e32 v3, 17, v3
	v_lshlrev_b32_e32 v11, 12, v4
	s_sub_i32 s1, s1, s70
	v_and_b32_e32 v10, 0x70, v8
	v_bitop3_b32 v8, v8, v9, s2 bitop3:0x6c
	v_or_b32_e32 v12, v11, v3
	v_readfirstlane_b32 s5, v208
	v_add3_u32 v13, v8, s1, v12
	s_mov_b32 m0, s5
	v_add_u32_e32 v12, s4, v12
	buffer_load_dwordx4 v13, s[44:47], 0 offen lds
	v_or_b32_e32 v13, 1, v7
	v_lshl_or_b32 v14, v13, 3, v4
	v_lshrrev_b32_e32 v15, 1, v14
	v_xor_b32_e32 v15, v15, v2
	v_lshlrev_b32_e32 v209, 10, v13
	v_lshlrev_b32_e32 v13, 4, v15
	v_and_b32_e32 v13, 0x70, v13
	v_lshlrev_b32_e32 v14, 12, v14
	v_readfirstlane_b32 s5, v209
	v_add3_u32 v15, v14, s1, v13
	s_mov_b32 m0, s5
	v_bitop3_b32 v9, v12, v10, v9 bitop3:0xf6
	buffer_load_dwordx4 v15, s[44:47], 0 offen lds
	v_or_b32_e32 v15, 2, v7
	v_lshl_or_b32 v16, v15, 3, v4
	v_lshrrev_b32_e32 v17, 1, v16
	v_xor_b32_e32 v17, v17, v2
	v_lshlrev_b32_e32 v210, 10, v15
	v_lshlrev_b32_e32 v15, 4, v17
	v_and_b32_e32 v15, 0x70, v15
	v_lshlrev_b32_e32 v16, 12, v16
	v_readfirstlane_b32 s5, v210
	v_or_b32_e32 v7, 3, v7
	v_add3_u32 v17, v16, s1, v15
	s_mov_b32 m0, s5
	v_lshl_or_b32 v4, v7, 3, v4
	buffer_load_dwordx4 v17, s[44:47], 0 offen lds
	v_lshrrev_b32_e32 v17, 1, v4
	v_xor_b32_e32 v17, v17, v2
	v_lshlrev_b32_e32 v211, 10, v7
	v_lshlrev_b32_e32 v7, 4, v17
	v_and_b32_e32 v7, 0x70, v7
	v_lshlrev_b32_e32 v4, 12, v4
	v_add3_u32 v17, v4, s1, v7
	v_readfirstlane_b32 s1, v211
	s_mov_b32 m0, s1
	v_add_u32_e32 v10, s4, v14
	buffer_load_dwordx4 v17, s[44:47], 0 offen lds
	v_add_u32_e32 v17, 0x8000, v208
	v_or_b32_e32 v10, v13, v10
	v_readfirstlane_b32 s1, v17
	s_mov_b32 m0, s1
	v_add_u32_e32 v4, s4, v4
	buffer_load_dwordx4 v9, s[44:47], 0 offen lds
	v_add_u32_e32 v9, 0x8000, v209
	v_or_b32_e32 v4, v7, v4
	v_readfirstlane_b32 s1, v9
	s_mov_b32 m0, s1
	v_add_u32_e32 v9, 0x8000, v210
	buffer_load_dwordx4 v10, s[44:47], 0 offen lds
	v_add_u32_e32 v10, s4, v16
	v_readfirstlane_b32 s1, v9
	v_add_u32_e32 v9, 0x8000, v211
	v_or_b32_e32 v10, v15, v10
	s_mov_b32 m0, s1
	v_readfirstlane_b32 s1, v9
	buffer_load_dwordx4 v10, s[44:47], 0 offen lds
	s_mov_b32 m0, s1
	s_lshl_b32 s1, s54, 20
	buffer_load_dwordx4 v4, s[44:47], 0 offen lds
	s_add_i32 s4, s57, s1
	v_bfe_u32 v205, v2, 4, 2
	v_and_b32_e32 v1, 15, v2
	v_lshrrev_b32_e32 v5, 1, v2
	v_bfe_u32 v6, v2, 1, 3
	v_ashrrev_i32_e32 v212, 8, v2
	s_lshl_b32 s17, s6, 8
	v_readlane_b32 s18, v230, 3
	v_readlane_b32 s19, v230, 4
	v_lshl_add_u32 v130, v212, 7, s17
	v_or_b32_e32 v130, v130, v1
	v_ashrrev_i32_e32 v131, 31, v130
	v_lshl_add_u64 v[130:131], v[130:131], 2, s[18:19]
	global_load_dword v224, v[130:131], off
	global_load_dword v225, v[130:131], off offset:64
	global_load_dword v226, v[130:131], off offset:128
	global_load_dword v227, v[130:131], off offset:192
	global_load_dword v228, v[130:131], off offset:256
	global_load_dword v231, v[130:131], off offset:320
	global_load_dword v254, v[130:131], off offset:384
	global_load_dword v255, v[130:131], off offset:448
	v_add_u32_e32 v2, s4, v3
	v_readlane_b32 s5, v229, 15
	v_add3_u32 v2, v2, v11, v7
	s_mul_i32 s4, s6, 0x1800000
	s_add_i32 s5, s5, s1
	v_subrev_u32_e32 v216, s4, v2
	v_add_u32_e32 v2, s5, v3
	v_readlane_b32 s5, v229, 17
	v_add3_u32 v2, v2, v11, v15
	s_add_i32 s5, s5, s1
	v_subrev_u32_e32 v217, s4, v2
	v_add_u32_e32 v2, s5, v3
	v_readlane_b32 s5, v229, 46
	v_add3_u32 v2, v2, v11, v13
	s_add_i32 s1, s1, s5
	v_subrev_u32_e32 v218, s4, v2
	v_add_u32_e32 v2, s1, v8
	v_readlane_b32 s1, v229, 14
	v_add3_u32 v2, v2, v3, v11
	s_add_i32 s1, s1, s0
	v_subrev_u32_e32 v219, s4, v2
	v_add_u32_e32 v2, s1, v3
	v_readlane_b32 s1, v229, 16
	s_add_i32 s1, s1, s0
	v_add3_u32 v220, v2, v11, v7
	v_add_u32_e32 v2, s1, v3
	v_readlane_b32 s1, v229, 18
	s_add_i32 s1, s1, s0
	v_add3_u32 v221, v2, v11, v15
	v_add_u32_e32 v2, s1, v3
	v_readlane_b32 s1, v229, 19
	s_add_i32 s0, s0, s1
	v_bitop3_b32 v5, v205, v5, 7 bitop3:0x78
	v_bitop3_b32 v6, v205, v6, 4 bitop3:0x36
	v_add3_u32 v222, v2, v11, v13
	v_add_u32_e32 v2, s0, v8
	v_mov_b32_e32 v34, 0
	v_lshlrev_b32_e32 v206, 7, v1
	v_lshlrev_b32_e32 v207, 13, v204
	s_mov_b32 s2, 0
	v_lshlrev_b32_e32 v213, 14, v212
	v_lshlrev_b32_e32 v214, 4, v5
	v_lshlrev_b32_e32 v215, 4, v6
	v_add3_u32 v223, v2, v3, v11
	s_mov_b32 s7, 0
	v_mov_b32_e32 v35, v34
	v_mov_b32_e32 v36, v34
	v_mov_b32_e32 v37, v34
	v_mov_b32_e32 v38, v34
	v_mov_b32_e32 v39, v34
	v_mov_b32_e32 v40, v34
	v_mov_b32_e32 v41, v34
	v_mov_b32_e32 v42, v34
	v_mov_b32_e32 v43, v34
	v_mov_b32_e32 v44, v34
	v_mov_b32_e32 v45, v34
	v_mov_b32_e32 v46, v34
	v_mov_b32_e32 v47, v34
	v_mov_b32_e32 v48, v34
	v_mov_b32_e32 v49, v34
	v_mov_b32_e32 v50, v34
	v_mov_b32_e32 v51, v34
	v_mov_b32_e32 v52, v34
	v_mov_b32_e32 v53, v34
	v_mov_b32_e32 v54, v34
	v_mov_b32_e32 v55, v34
	v_mov_b32_e32 v56, v34
	v_mov_b32_e32 v57, v34
	v_mov_b32_e32 v58, v34
	v_mov_b32_e32 v59, v34
	v_mov_b32_e32 v60, v34
	v_mov_b32_e32 v61, v34
	v_mov_b32_e32 v62, v34
	v_mov_b32_e32 v63, v34
	v_mov_b32_e32 v64, v34
	v_mov_b32_e32 v65, v34
	v_mov_b32_e32 v66, v34
	v_mov_b32_e32 v67, v34
	v_mov_b32_e32 v68, v34
	v_mov_b32_e32 v69, v34
	v_mov_b32_e32 v70, v34
	v_mov_b32_e32 v71, v34
	v_mov_b32_e32 v72, v34
	v_mov_b32_e32 v73, v34
	v_mov_b32_e32 v74, v34
	v_mov_b32_e32 v75, v34
	v_mov_b32_e32 v76, v34
	v_mov_b32_e32 v77, v34
	v_mov_b32_e32 v78, v34
	v_mov_b32_e32 v79, v34
	v_mov_b32_e32 v80, v34
	v_mov_b32_e32 v81, v34
	v_mov_b32_e32 v82, v34
	v_mov_b32_e32 v83, v34
	v_mov_b32_e32 v84, v34
	v_mov_b32_e32 v85, v34
	v_mov_b32_e32 v86, v34
	v_mov_b32_e32 v87, v34
	v_mov_b32_e32 v88, v34
	v_mov_b32_e32 v89, v34
	v_mov_b32_e32 v90, v34
	v_mov_b32_e32 v91, v34
	v_mov_b32_e32 v92, v34
	v_mov_b32_e32 v93, v34
	v_mov_b32_e32 v94, v34
	v_mov_b32_e32 v95, v34
	v_mov_b32_e32 v96, v34
	v_mov_b32_e32 v97, v34
	v_mov_b32_e32 v98, v34
	v_mov_b32_e32 v99, v34
	v_mov_b32_e32 v100, v34
	v_mov_b32_e32 v101, v34
	v_mov_b32_e32 v102, v34
	v_mov_b32_e32 v103, v34
	v_mov_b32_e32 v104, v34
	v_mov_b32_e32 v105, v34
	v_mov_b32_e32 v106, v34
	v_mov_b32_e32 v107, v34
	v_mov_b32_e32 v108, v34
	v_mov_b32_e32 v109, v34
	v_mov_b32_e32 v110, v34
	v_mov_b32_e32 v111, v34
	v_mov_b32_e32 v112, v34
	v_mov_b32_e32 v113, v34
	v_mov_b32_e32 v114, v34
	v_mov_b32_e32 v115, v34
	v_mov_b32_e32 v116, v34
	v_mov_b32_e32 v117, v34
	v_mov_b32_e32 v118, v34
	v_mov_b32_e32 v119, v34
	v_mov_b32_e32 v120, v34
	v_mov_b32_e32 v121, v34
	v_mov_b32_e32 v122, v34
	v_mov_b32_e32 v123, v34
	v_mov_b32_e32 v124, v34
	v_mov_b32_e32 v125, v34
	v_mov_b32_e32 v126, v34
	v_mov_b32_e32 v127, v34
	v_mov_b32_e32 v128, v34
	v_mov_b32_e32 v129, v34
	v_mov_b32_e32 v30, v34
	v_mov_b32_e32 v31, v34
	v_mov_b32_e32 v32, v34
	v_mov_b32_e32 v33, v34
	v_mov_b32_e32 v26, v34
	v_mov_b32_e32 v27, v34
	v_mov_b32_e32 v28, v34
	v_mov_b32_e32 v29, v34
	v_mov_b32_e32 v22, v34
	v_mov_b32_e32 v23, v34
	v_mov_b32_e32 v24, v34
	v_mov_b32_e32 v25, v34
	v_mov_b32_e32 v18, v34
	v_mov_b32_e32 v19, v34
	v_mov_b32_e32 v20, v34
	v_mov_b32_e32 v21, v34
	v_mov_b32_e32 v14, v34
	v_mov_b32_e32 v15, v34
	v_mov_b32_e32 v16, v34
	v_mov_b32_e32 v17, v34
	v_mov_b32_e32 v10, v34
	v_mov_b32_e32 v11, v34
	v_mov_b32_e32 v12, v34
	v_mov_b32_e32 v13, v34
	v_mov_b32_e32 v6, v34
	v_mov_b32_e32 v7, v34
	v_mov_b32_e32 v8, v34
	v_mov_b32_e32 v9, v34
	v_mov_b32_e32 v2, v34
	v_mov_b32_e32 v3, v34
	v_mov_b32_e32 v4, v34
	v_mov_b32_e32 v5, v34
	v_readlane_b32 s61, v230, 19
	v_readlane_b32 s62, v230, 20
	v_readlane_b32 s63, v230, 21
	v_readlane_b32 s64, v230, 22
	v_readlane_b32 s65, v230, 23
	v_readlane_b32 s66, v230, 24
	v_readlane_b32 s67, v230, 25
	v_readlane_b32 s68, v230, 26
	v_readlane_b32 s69, v230, 27
	v_readlane_b32 s71, v230, 29
	v_readlane_b32 s72, v230, 30
	v_readlane_b32 s73, v230, 31
	v_readlane_b32 s74, v230, 32
	v_readlane_b32 s75, v230, 33
	v_readfirstlane_b32 s12, v208
	v_readfirstlane_b32 s16, v212
	v_add3_u32 v250, v213, v206, v214
	v_add3_u32 v251, v213, v206, v215
	v_add3_u32 v252, v207, v206, v214
	v_add3_u32 v253, v207, v206, v215
	s_mov_b32 s10, 0
	s_mov_b32 s11, 0
	s_waitcnt vmcnt(0)
	s_barrier
	s_add_i32 s14, s12, 0x10000
	s_mov_b32 m0, s14
	s_nop 0
	buffer_load_dwordx4 v223, s[44:47], s11 offen lds
	s_add_u32 m0, s14, 0x400
	s_nop 0
	buffer_load_dwordx4 v222, s[44:47], s11 offen lds
	s_add_u32 m0, s14, 0x800
	s_nop 0
	buffer_load_dwordx4 v221, s[44:47], s11 offen lds
	s_add_u32 m0, s14, 0xc00
	s_nop 0
	buffer_load_dwordx4 v220, s[44:47], s11 offen lds
	s_add_u32 m0, s14, 0x8000
	s_nop 0
	buffer_load_dwordx4 v219, s[44:47], s11 offen lds
	s_add_u32 m0, s14, 0x8400
	s_nop 0
	buffer_load_dwordx4 v218, s[44:47], s11 offen lds
	s_add_u32 m0, s14, 0x8800
	s_nop 0
	buffer_load_dwordx4 v217, s[44:47], s11 offen lds
	s_add_u32 m0, s14, 0x8c00
	s_nop 0
	buffer_load_dwordx4 v216, s[44:47], s11 offen lds
	s_movk_i32 s11, 0x80
	ds_read_b128 v[162:165], v252 offset:32768
	ds_read_b128 v[166:169], v252 offset:34816
	ds_read_b128 v[170:173], v252 offset:36864
	ds_read_b128 v[174:177], v252 offset:38912
	ds_read_b128 v[146:149], v250 offset:8192
	ds_read_b128 v[150:153], v250 offset:10240
	ds_read_b128 v[154:157], v250 offset:12288
	ds_read_b128 v[158:161], v250 offset:14336
	ds_read_b128 v[130:133], v250
	ds_read_b128 v[134:137], v250 offset:2048
	ds_read_b128 v[138:141], v250 offset:4096
	ds_read_b128 v[142:145], v250 offset:6144
	s_movk_i32 s15, 30

.LBB0_160:
	s_lshr_b32 s10, s8, 2
	s_cmp_eq_u32 s10, 4
	s_cbranch_scc1 .Lp1_oldepi
	v_and_b32_e32 v130, 63, v194
	v_lshrrev_b32_e32 v134, 6, v194
	v_lshrrev_b32_e32 v131, 3, v130
	v_and_b32_e32 v132, 7, v130
	v_xor_b32_e32 v133, v132, v131
	v_lshlrev_b32_e32 v133, 4, v133
	v_lshl_add_u32 v135, v131, 7, v133
	v_lshl_add_u32 v135, v134, 11, v135
	v_add_u32_e32 v135, 0x20000, v135
	v_and_b32_e32 v138, 15, v130
	v_lshrrev_b32_e32 v137, 4, v130
	v_lshrrev_b32_e32 v133, 1, v137
	v_bitop3_b32 v133, v133, v138, 7 bitop3:0x78
	v_lshlrev_b32_e32 v133, 4, v133
	v_lshl_add_u32 v136, v138, 7, v133
	v_and_b32_e32 v133, 1, v137
	v_lshl_add_u32 v136, v133, 3, v136
	v_lshl_add_u32 v136, v134, 11, v136
	v_add_u32_e32 v136, 0x20000, v136
	v_lshl_add_u32 v139, v212, 7, v131
	v_mul_u32_u24_e32 v139, 0x3000, v139
	v_lshl_add_u32 v139, v204, 7, v139
	v_lshl_add_u32 v139, v132, 4, v139
	s_sub_u32 s11, s92, s44
	s_mul_i32 s12, s6, 0x300000
	s_add_u32 s11, s11, s12
	s_lshl_b32 s12, s8, 9
	s_add_u32 s11, s11, s12
	s_cmp_lt_u32 s8, 4
	s_cselect_b64 s[12:13], -1, 0
	v_mov_b32_e32 v176, 1.0
	s_nop 0
	v_cndmask_b32_e64 v176, v176, v200, s[12:13]
	s_cmp_eq_u32 s10, 3
	s_cbranch_scc1 .Lp1_epi_act
	s_cmp_eq_u32 s10, 5
	s_cbranch_scc1 .Lp1_epi_act
	v_mul_f32_e32 v177, v176, v224
	v_mul_f32_e32 v126, v177, v126
	v_mul_f32_e32 v127, v177, v127
	v_mul_f32_e32 v128, v177, v128
	v_mul_f32_e32 v129, v177, v129
	v_mul_f32_e32 v122, v177, v122
	v_mul_f32_e32 v123, v177, v123
	v_mul_f32_e32 v124, v177, v124
	v_mul_f32_e32 v125, v177, v125
	v_mul_f32_e32 v118, v177, v118
	v_mul_f32_e32 v119, v177, v119
	v_mul_f32_e32 v120, v177, v120
	v_mul_f32_e32 v121, v177, v121
	v_mul_f32_e32 v114, v177, v114
	v_mul_f32_e32 v115, v177, v115
	v_mul_f32_e32 v116, v177, v116
	v_mul_f32_e32 v117, v177, v117
	v_cvt_pk_bf16_f32 v140, v126, v127
	v_cvt_pk_bf16_f32 v141, v128, v129
	v_cvt_pk_bf16_f32 v142, v122, v123
	v_cvt_pk_bf16_f32 v143, v124, v125
	v_cvt_pk_bf16_f32 v144, v118, v119
	v_cvt_pk_bf16_f32 v145, v120, v121
	v_cvt_pk_bf16_f32 v146, v114, v115
	v_cvt_pk_bf16_f32 v147, v116, v117
	ds_write_b64 v136, v[140:141]
	v_xor_b32_e32 v173, 0x20, v136
	ds_write_b64 v173, v[142:143]
	v_xor_b32_e32 v174, 0x40, v136
	ds_write_b64 v174, v[144:145]
	v_xor_b32_e32 v175, 0x60, v136
	ds_write_b64 v175, v[146:147]
	ds_read_b128 v[148:151], v135
	ds_read_b128 v[152:155], v135 offset:1024
	v_mul_f32_e32 v177, v176, v225
	v_mul_f32_e32 v110, v177, v110
	v_mul_f32_e32 v111, v177, v111
	v_mul_f32_e32 v112, v177, v112
	v_mul_f32_e32 v113, v177, v113
	v_mul_f32_e32 v106, v177, v106
	v_mul_f32_e32 v107, v177, v107
	v_mul_f32_e32 v108, v177, v108
	v_mul_f32_e32 v109, v177, v109
	v_mul_f32_e32 v102, v177, v102
	v_mul_f32_e32 v103, v177, v103
	v_mul_f32_e32 v104, v177, v104
	v_mul_f32_e32 v105, v177, v105
	v_mul_f32_e32 v98, v177, v98
	v_mul_f32_e32 v99, v177, v99
	v_mul_f32_e32 v100, v177, v100
	v_mul_f32_e32 v101, v177, v101
	v_cvt_pk_bf16_f32 v164, v110, v111
	v_cvt_pk_bf16_f32 v165, v112, v113
	v_cvt_pk_bf16_f32 v166, v106, v107
	v_cvt_pk_bf16_f32 v167, v108, v109
	v_cvt_pk_bf16_f32 v168, v102, v103
	v_cvt_pk_bf16_f32 v169, v104, v105
	v_cvt_pk_bf16_f32 v170, v98, v99
	v_cvt_pk_bf16_f32 v171, v100, v101
	ds_write_b64 v136, v[164:165]
	v_xor_b32_e32 v173, 0x20, v136
	ds_write_b64 v173, v[166:167]
	v_xor_b32_e32 v174, 0x40, v136
	ds_write_b64 v174, v[168:169]
	v_xor_b32_e32 v175, 0x60, v136
	ds_write_b64 v175, v[170:171]
	ds_read_b128 v[156:159], v135
	ds_read_b128 v[160:163], v135 offset:1024
	s_waitcnt lgkmcnt(6)
	buffer_store_dwordx4 v[148:151], v139, s[44:47], s11 offen
	s_add_u32 s11, s11, 0x18000
	buffer_store_dwordx4 v[152:155], v139, s[44:47], s11 offen
	s_add_u32 s11, s11, 0x18000
	v_mul_f32_e32 v177, v176, v226
	v_mul_f32_e32 v94, v177, v94
	v_mul_f32_e32 v95, v177, v95
	v_mul_f32_e32 v96, v177, v96
	v_mul_f32_e32 v97, v177, v97
	v_mul_f32_e32 v90, v177, v90
	v_mul_f32_e32 v91, v177, v91
	v_mul_f32_e32 v92, v177, v92
	v_mul_f32_e32 v93, v177, v93
	v_mul_f32_e32 v86, v177, v86
	v_mul_f32_e32 v87, v177, v87
	v_mul_f32_e32 v88, v177, v88
	v_mul_f32_e32 v89, v177, v89
	v_mul_f32_e32 v82, v177, v82
	v_mul_f32_e32 v83, v177, v83
	v_mul_f32_e32 v84, v177, v84
	v_mul_f32_e32 v85, v177, v85
	v_cvt_pk_bf16_f32 v140, v94, v95
	v_cvt_pk_bf16_f32 v141, v96, v97
	v_cvt_pk_bf16_f32 v142, v90, v91
	v_cvt_pk_bf16_f32 v143, v92, v93
	v_cvt_pk_bf16_f32 v144, v86, v87
	v_cvt_pk_bf16_f32 v145, v88, v89
	v_cvt_pk_bf16_f32 v146, v82, v83
	v_cvt_pk_bf16_f32 v147, v84, v85
	ds_write_b64 v136, v[140:141]
	v_xor_b32_e32 v173, 0x20, v136
	ds_write_b64 v173, v[142:143]
	v_xor_b32_e32 v174, 0x40, v136
	ds_write_b64 v174, v[144:145]
	v_xor_b32_e32 v175, 0x60, v136
	ds_write_b64 v175, v[146:147]
	ds_read_b128 v[148:151], v135
	ds_read_b128 v[152:155], v135 offset:1024
	s_waitcnt lgkmcnt(6)
	buffer_store_dwordx4 v[156:159], v139, s[44:47], s11 offen
	s_add_u32 s11, s11, 0x18000
	buffer_store_dwordx4 v[160:163], v139, s[44:47], s11 offen
	s_add_u32 s11, s11, 0x18000
	v_mul_f32_e32 v177, v176, v227
	v_mul_f32_e32 v78, v177, v78
	v_mul_f32_e32 v79, v177, v79
	v_mul_f32_e32 v80, v177, v80
	v_mul_f32_e32 v81, v177, v81
	v_mul_f32_e32 v74, v177, v74
	v_mul_f32_e32 v75, v177, v75
	v_mul_f32_e32 v76, v177, v76
	v_mul_f32_e32 v77, v177, v77
	v_mul_f32_e32 v70, v177, v70
	v_mul_f32_e32 v71, v177, v71
	v_mul_f32_e32 v72, v177, v72
	v_mul_f32_e32 v73, v177, v73
	v_mul_f32_e32 v66, v177, v66
	v_mul_f32_e32 v67, v177, v67
	v_mul_f32_e32 v68, v177, v68
	v_mul_f32_e32 v69, v177, v69
	v_cvt_pk_bf16_f32 v164, v78, v79
	v_cvt_pk_bf16_f32 v165, v80, v81
	v_cvt_pk_bf16_f32 v166, v74, v75
	v_cvt_pk_bf16_f32 v167, v76, v77
	v_cvt_pk_bf16_f32 v168, v70, v71
	v_cvt_pk_bf16_f32 v169, v72, v73
	v_cvt_pk_bf16_f32 v170, v66, v67
	v_cvt_pk_bf16_f32 v171, v68, v69
	ds_write_b64 v136, v[164:165]
	v_xor_b32_e32 v173, 0x20, v136
	ds_write_b64 v173, v[166:167]
	v_xor_b32_e32 v174, 0x40, v136
	ds_write_b64 v174, v[168:169]
	v_xor_b32_e32 v175, 0x60, v136
	ds_write_b64 v175, v[170:171]
	ds_read_b128 v[156:159], v135
	ds_read_b128 v[160:163], v135 offset:1024
	s_waitcnt lgkmcnt(6)
	buffer_store_dwordx4 v[148:151], v139, s[44:47], s11 offen
	s_add_u32 s11, s11, 0x18000
	buffer_store_dwordx4 v[152:155], v139, s[44:47], s11 offen
	s_add_u32 s11, s11, 0x18000
	v_mul_f32_e32 v177, v176, v228
	v_mul_f32_e32 v62, v177, v62
	v_mul_f32_e32 v63, v177, v63
	v_mul_f32_e32 v64, v177, v64
	v_mul_f32_e32 v65, v177, v65
	v_mul_f32_e32 v58, v177, v58
	v_mul_f32_e32 v59, v177, v59
	v_mul_f32_e32 v60, v177, v60
	v_mul_f32_e32 v61, v177, v61
	v_mul_f32_e32 v54, v177, v54
	v_mul_f32_e32 v55, v177, v55
	v_mul_f32_e32 v56, v177, v56
	v_mul_f32_e32 v57, v177, v57
	v_mul_f32_e32 v50, v177, v50
	v_mul_f32_e32 v51, v177, v51
	v_mul_f32_e32 v52, v177, v52
	v_mul_f32_e32 v53, v177, v53
	v_cvt_pk_bf16_f32 v140, v62, v63
	v_cvt_pk_bf16_f32 v141, v64, v65
	v_cvt_pk_bf16_f32 v142, v58, v59
	v_cvt_pk_bf16_f32 v143, v60, v61
	v_cvt_pk_bf16_f32 v144, v54, v55
	v_cvt_pk_bf16_f32 v145, v56, v57
	v_cvt_pk_bf16_f32 v146, v50, v51
	v_cvt_pk_bf16_f32 v147, v52, v53
	ds_write_b64 v136, v[140:141]
	v_xor_b32_e32 v173, 0x20, v136
	ds_write_b64 v173, v[142:143]
	v_xor_b32_e32 v174, 0x40, v136
	ds_write_b64 v174, v[144:145]
	v_xor_b32_e32 v175, 0x60, v136
	ds_write_b64 v175, v[146:147]
	ds_read_b128 v[148:151], v135
	ds_read_b128 v[152:155], v135 offset:1024
	s_waitcnt lgkmcnt(6)
	buffer_store_dwordx4 v[156:159], v139, s[44:47], s11 offen
	s_add_u32 s11, s11, 0x18000
	buffer_store_dwordx4 v[160:163], v139, s[44:47], s11 offen
	s_add_u32 s11, s11, 0x18000
	v_mul_f32_e32 v177, v176, v231
	v_mul_f32_e32 v46, v177, v46
	v_mul_f32_e32 v47, v177, v47
	v_mul_f32_e32 v48, v177, v48
	v_mul_f32_e32 v49, v177, v49
	v_mul_f32_e32 v42, v177, v42
	v_mul_f32_e32 v43, v177, v43
	v_mul_f32_e32 v44, v177, v44
	v_mul_f32_e32 v45, v177, v45
	v_mul_f32_e32 v38, v177, v38
	v_mul_f32_e32 v39, v177, v39
	v_mul_f32_e32 v40, v177, v40
	v_mul_f32_e32 v41, v177, v41
	v_mul_f32_e32 v34, v177, v34
	v_mul_f32_e32 v35, v177, v35
	v_mul_f32_e32 v36, v177, v36
	v_mul_f32_e32 v37, v177, v37
	v_cvt_pk_bf16_f32 v164, v46, v47
	v_cvt_pk_bf16_f32 v165, v48, v49
	v_cvt_pk_bf16_f32 v166, v42, v43
	v_cvt_pk_bf16_f32 v167, v44, v45
	v_cvt_pk_bf16_f32 v168, v38, v39
	v_cvt_pk_bf16_f32 v169, v40, v41
	v_cvt_pk_bf16_f32 v170, v34, v35
	v_cvt_pk_bf16_f32 v171, v36, v37
	ds_write_b64 v136, v[164:165]
	v_xor_b32_e32 v173, 0x20, v136
	ds_write_b64 v173, v[166:167]
	v_xor_b32_e32 v174, 0x40, v136
	ds_write_b64 v174, v[168:169]
	v_xor_b32_e32 v175, 0x60, v136
	ds_write_b64 v175, v[170:171]
	ds_read_b128 v[156:159], v135
	ds_read_b128 v[160:163], v135 offset:1024
	s_waitcnt lgkmcnt(6)
	buffer_store_dwordx4 v[148:151], v139, s[44:47], s11 offen
	s_add_u32 s11, s11, 0x18000
	buffer_store_dwordx4 v[152:155], v139, s[44:47], s11 offen
	s_add_u32 s11, s11, 0x18000
	v_mul_f32_e32 v177, v176, v254
	v_mul_f32_e32 v30, v177, v30
	v_mul_f32_e32 v31, v177, v31
	v_mul_f32_e32 v32, v177, v32
	v_mul_f32_e32 v33, v177, v33
	v_mul_f32_e32 v26, v177, v26
	v_mul_f32_e32 v27, v177, v27
	v_mul_f32_e32 v28, v177, v28
	v_mul_f32_e32 v29, v177, v29
	v_mul_f32_e32 v22, v177, v22
	v_mul_f32_e32 v23, v177, v23
	v_mul_f32_e32 v24, v177, v24
	v_mul_f32_e32 v25, v177, v25
	v_mul_f32_e32 v18, v177, v18
	v_mul_f32_e32 v19, v177, v19
	v_mul_f32_e32 v20, v177, v20
	v_mul_f32_e32 v21, v177, v21
	v_cvt_pk_bf16_f32 v140, v30, v31
	v_cvt_pk_bf16_f32 v141, v32, v33
	v_cvt_pk_bf16_f32 v142, v26, v27
	v_cvt_pk_bf16_f32 v143, v28, v29
	v_cvt_pk_bf16_f32 v144, v22, v23
	v_cvt_pk_bf16_f32 v145, v24, v25
	v_cvt_pk_bf16_f32 v146, v18, v19
	v_cvt_pk_bf16_f32 v147, v20, v21
	ds_write_b64 v136, v[140:141]
	v_xor_b32_e32 v173, 0x20, v136
	ds_write_b64 v173, v[142:143]
	v_xor_b32_e32 v174, 0x40, v136
	ds_write_b64 v174, v[144:145]
	v_xor_b32_e32 v175, 0x60, v136
	ds_write_b64 v175, v[146:147]
	ds_read_b128 v[148:151], v135
	ds_read_b128 v[152:155], v135 offset:1024
	s_waitcnt lgkmcnt(6)
	buffer_store_dwordx4 v[156:159], v139, s[44:47], s11 offen
	s_add_u32 s11, s11, 0x18000
	buffer_store_dwordx4 v[160:163], v139, s[44:47], s11 offen
	s_add_u32 s11, s11, 0x18000
	v_mul_f32_e32 v177, v176, v255
	v_mul_f32_e32 v14, v177, v14
	v_mul_f32_e32 v15, v177, v15
	v_mul_f32_e32 v16, v177, v16
	v_mul_f32_e32 v17, v177, v17
	v_mul_f32_e32 v10, v177, v10
	v_mul_f32_e32 v11, v177, v11
	v_mul_f32_e32 v12, v177, v12
	v_mul_f32_e32 v13, v177, v13
	v_mul_f32_e32 v6, v177, v6
	v_mul_f32_e32 v7, v177, v7
	v_mul_f32_e32 v8, v177, v8
	v_mul_f32_e32 v9, v177, v9
	v_mul_f32_e32 v2, v177, v2
	v_mul_f32_e32 v3, v177, v3
	v_mul_f32_e32 v4, v177, v4
	v_mul_f32_e32 v5, v177, v5
	v_cvt_pk_bf16_f32 v164, v14, v15
	v_cvt_pk_bf16_f32 v165, v16, v17
	v_cvt_pk_bf16_f32 v166, v10, v11
	v_cvt_pk_bf16_f32 v167, v12, v13
	v_cvt_pk_bf16_f32 v168, v6, v7
	v_cvt_pk_bf16_f32 v169, v8, v9
	v_cvt_pk_bf16_f32 v170, v2, v3
	v_cvt_pk_bf16_f32 v171, v4, v5
	ds_write_b64 v136, v[164:165]
	v_xor_b32_e32 v173, 0x20, v136
	ds_write_b64 v173, v[166:167]
	v_xor_b32_e32 v174, 0x40, v136
	ds_write_b64 v174, v[168:169]
	v_xor_b32_e32 v175, 0x60, v136
	ds_write_b64 v175, v[170:171]
	ds_read_b128 v[156:159], v135
	ds_read_b128 v[160:163], v135 offset:1024
	s_waitcnt lgkmcnt(6)
	buffer_store_dwordx4 v[148:151], v139, s[44:47], s11 offen
	s_add_u32 s11, s11, 0x18000
	buffer_store_dwordx4 v[152:155], v139, s[44:47], s11 offen
	s_add_u32 s11, s11, 0x18000
	s_waitcnt lgkmcnt(0)
	buffer_store_dwordx4 v[156:159], v139, s[44:47], s11 offen
	s_add_u32 s11, s11, 0x18000
	buffer_store_dwordx4 v[160:163], v139, s[44:47], s11 offen
	s_branch .LBB0_141
.Lp1_epi_act:
	v_mul_f32_e32 v177, v176, v224
	v_mul_f32_e32 v126, v177, v126
	v_mul_f32_e32 v127, v177, v127
	v_mul_f32_e32 v128, v177, v128
	v_mul_f32_e32 v129, v177, v129
	v_mul_f32_e32 v122, v177, v122
	v_mul_f32_e32 v123, v177, v123
	v_mul_f32_e32 v124, v177, v124
	v_mul_f32_e32 v125, v177, v125
	v_mul_f32_e32 v118, v177, v118
	v_mul_f32_e32 v119, v177, v119
	v_mul_f32_e32 v120, v177, v120
	v_mul_f32_e32 v121, v177, v121
	v_mul_f32_e32 v114, v177, v114
	v_mul_f32_e32 v115, v177, v115
	v_mul_f32_e32 v116, v177, v116
	v_mul_f32_e32 v117, v177, v117
	v_mul_f32_e32 v178, 0xbfb8aa3b, v126
	v_mul_f32_e32 v179, 0xbfb8aa3b, v127
	v_mul_f32_e32 v180, 0xbfb8aa3b, v128
	v_mul_f32_e32 v181, 0xbfb8aa3b, v129
	v_exp_f32_e32 v178, v178
	v_exp_f32_e32 v179, v179
	v_exp_f32_e32 v180, v180
	v_exp_f32_e32 v181, v181
	v_add_f32_e32 v178, 1.0, v178
	v_add_f32_e32 v179, 1.0, v179
	v_add_f32_e32 v180, 1.0, v180
	v_add_f32_e32 v181, 1.0, v181
	v_rcp_f32_e32 v178, v178
	v_rcp_f32_e32 v179, v179
	v_rcp_f32_e32 v180, v180
	v_rcp_f32_e32 v181, v181
	v_mul_f32_e32 v126, v126, v178
	v_mul_f32_e32 v127, v127, v179
	v_mul_f32_e32 v128, v128, v180
	v_mul_f32_e32 v129, v129, v181
	v_mul_f32_e32 v178, 0xbfb8aa3b, v122
	v_mul_f32_e32 v179, 0xbfb8aa3b, v123
	v_mul_f32_e32 v180, 0xbfb8aa3b, v124
	v_mul_f32_e32 v181, 0xbfb8aa3b, v125
	v_exp_f32_e32 v178, v178
	v_exp_f32_e32 v179, v179
	v_exp_f32_e32 v180, v180
	v_exp_f32_e32 v181, v181
	v_add_f32_e32 v178, 1.0, v178
	v_add_f32_e32 v179, 1.0, v179
	v_add_f32_e32 v180, 1.0, v180
	v_add_f32_e32 v181, 1.0, v181
	v_rcp_f32_e32 v178, v178
	v_rcp_f32_e32 v179, v179
	v_rcp_f32_e32 v180, v180
	v_rcp_f32_e32 v181, v181
	v_mul_f32_e32 v122, v122, v178
	v_mul_f32_e32 v123, v123, v179
	v_mul_f32_e32 v124, v124, v180
	v_mul_f32_e32 v125, v125, v181
	v_mul_f32_e32 v178, 0xbfb8aa3b, v118
	v_mul_f32_e32 v179, 0xbfb8aa3b, v119
	v_mul_f32_e32 v180, 0xbfb8aa3b, v120
	v_mul_f32_e32 v181, 0xbfb8aa3b, v121
	v_exp_f32_e32 v178, v178
	v_exp_f32_e32 v179, v179
	v_exp_f32_e32 v180, v180
	v_exp_f32_e32 v181, v181
	v_add_f32_e32 v178, 1.0, v178
	v_add_f32_e32 v179, 1.0, v179
	v_add_f32_e32 v180, 1.0, v180
	v_add_f32_e32 v181, 1.0, v181
	v_rcp_f32_e32 v178, v178
	v_rcp_f32_e32 v179, v179
	v_rcp_f32_e32 v180, v180
	v_rcp_f32_e32 v181, v181
	v_mul_f32_e32 v118, v118, v178
	v_mul_f32_e32 v119, v119, v179
	v_mul_f32_e32 v120, v120, v180
	v_mul_f32_e32 v121, v121, v181
	v_mul_f32_e32 v178, 0xbfb8aa3b, v114
	v_mul_f32_e32 v179, 0xbfb8aa3b, v115
	v_mul_f32_e32 v180, 0xbfb8aa3b, v116
	v_mul_f32_e32 v181, 0xbfb8aa3b, v117
	v_exp_f32_e32 v178, v178
	v_exp_f32_e32 v179, v179
	v_exp_f32_e32 v180, v180
	v_exp_f32_e32 v181, v181
	v_add_f32_e32 v178, 1.0, v178
	v_add_f32_e32 v179, 1.0, v179
	v_add_f32_e32 v180, 1.0, v180
	v_add_f32_e32 v181, 1.0, v181
	v_rcp_f32_e32 v178, v178
	v_rcp_f32_e32 v179, v179
	v_rcp_f32_e32 v180, v180
	v_rcp_f32_e32 v181, v181
	v_mul_f32_e32 v114, v114, v178
	v_mul_f32_e32 v115, v115, v179
	v_mul_f32_e32 v116, v116, v180
	v_mul_f32_e32 v117, v117, v181
	v_cvt_pk_bf16_f32 v140, v126, v127
	v_cvt_pk_bf16_f32 v141, v128, v129
	v_cvt_pk_bf16_f32 v142, v122, v123
	v_cvt_pk_bf16_f32 v143, v124, v125
	v_cvt_pk_bf16_f32 v144, v118, v119
	v_cvt_pk_bf16_f32 v145, v120, v121
	v_cvt_pk_bf16_f32 v146, v114, v115
	v_cvt_pk_bf16_f32 v147, v116, v117
	ds_write_b64 v136, v[140:141]
	v_xor_b32_e32 v173, 0x20, v136
	ds_write_b64 v173, v[142:143]
	v_xor_b32_e32 v174, 0x40, v136
	ds_write_b64 v174, v[144:145]
	v_xor_b32_e32 v175, 0x60, v136
	ds_write_b64 v175, v[146:147]
	ds_read_b128 v[148:151], v135
	ds_read_b128 v[152:155], v135 offset:1024
	v_mul_f32_e32 v177, v176, v225
	v_mul_f32_e32 v110, v177, v110
	v_mul_f32_e32 v111, v177, v111
	v_mul_f32_e32 v112, v177, v112
	v_mul_f32_e32 v113, v177, v113
	v_mul_f32_e32 v106, v177, v106
	v_mul_f32_e32 v107, v177, v107
	v_mul_f32_e32 v108, v177, v108
	v_mul_f32_e32 v109, v177, v109
	v_mul_f32_e32 v102, v177, v102
	v_mul_f32_e32 v103, v177, v103
	v_mul_f32_e32 v104, v177, v104
	v_mul_f32_e32 v105, v177, v105
	v_mul_f32_e32 v98, v177, v98
	v_mul_f32_e32 v99, v177, v99
	v_mul_f32_e32 v100, v177, v100
	v_mul_f32_e32 v101, v177, v101
	v_mul_f32_e32 v178, 0xbfb8aa3b, v110
	v_mul_f32_e32 v179, 0xbfb8aa3b, v111
	v_mul_f32_e32 v180, 0xbfb8aa3b, v112
	v_mul_f32_e32 v181, 0xbfb8aa3b, v113
	v_exp_f32_e32 v178, v178
	v_exp_f32_e32 v179, v179
	v_exp_f32_e32 v180, v180
	v_exp_f32_e32 v181, v181
	v_add_f32_e32 v178, 1.0, v178
	v_add_f32_e32 v179, 1.0, v179
	v_add_f32_e32 v180, 1.0, v180
	v_add_f32_e32 v181, 1.0, v181
	v_rcp_f32_e32 v178, v178
	v_rcp_f32_e32 v179, v179
	v_rcp_f32_e32 v180, v180
	v_rcp_f32_e32 v181, v181
	v_mul_f32_e32 v110, v110, v178
	v_mul_f32_e32 v111, v111, v179
	v_mul_f32_e32 v112, v112, v180
	v_mul_f32_e32 v113, v113, v181
	v_mul_f32_e32 v178, 0xbfb8aa3b, v106
	v_mul_f32_e32 v179, 0xbfb8aa3b, v107
	v_mul_f32_e32 v180, 0xbfb8aa3b, v108
	v_mul_f32_e32 v181, 0xbfb8aa3b, v109
	v_exp_f32_e32 v178, v178
	v_exp_f32_e32 v179, v179
	v_exp_f32_e32 v180, v180
	v_exp_f32_e32 v181, v181
	v_add_f32_e32 v178, 1.0, v178
	v_add_f32_e32 v179, 1.0, v179
	v_add_f32_e32 v180, 1.0, v180
	v_add_f32_e32 v181, 1.0, v181
	v_rcp_f32_e32 v178, v178
	v_rcp_f32_e32 v179, v179
	v_rcp_f32_e32 v180, v180
	v_rcp_f32_e32 v181, v181
	v_mul_f32_e32 v106, v106, v178
	v_mul_f32_e32 v107, v107, v179
	v_mul_f32_e32 v108, v108, v180
	v_mul_f32_e32 v109, v109, v181
	v_mul_f32_e32 v178, 0xbfb8aa3b, v102
	v_mul_f32_e32 v179, 0xbfb8aa3b, v103
	v_mul_f32_e32 v180, 0xbfb8aa3b, v104
	v_mul_f32_e32 v181, 0xbfb8aa3b, v105
	v_exp_f32_e32 v178, v178
	v_exp_f32_e32 v179, v179
	v_exp_f32_e32 v180, v180
	v_exp_f32_e32 v181, v181
	v_add_f32_e32 v178, 1.0, v178
	v_add_f32_e32 v179, 1.0, v179
	v_add_f32_e32 v180, 1.0, v180
	v_add_f32_e32 v181, 1.0, v181
	v_rcp_f32_e32 v178, v178
	v_rcp_f32_e32 v179, v179
	v_rcp_f32_e32 v180, v180
	v_rcp_f32_e32 v181, v181
	v_mul_f32_e32 v102, v102, v178
	v_mul_f32_e32 v103, v103, v179
	v_mul_f32_e32 v104, v104, v180
	v_mul_f32_e32 v105, v105, v181
	v_mul_f32_e32 v178, 0xbfb8aa3b, v98
	v_mul_f32_e32 v179, 0xbfb8aa3b, v99
	v_mul_f32_e32 v180, 0xbfb8aa3b, v100
	v_mul_f32_e32 v181, 0xbfb8aa3b, v101
	v_exp_f32_e32 v178, v178
	v_exp_f32_e32 v179, v179
	v_exp_f32_e32 v180, v180
	v_exp_f32_e32 v181, v181
	v_add_f32_e32 v178, 1.0, v178
	v_add_f32_e32 v179, 1.0, v179
	v_add_f32_e32 v180, 1.0, v180
	v_add_f32_e32 v181, 1.0, v181
	v_rcp_f32_e32 v178, v178
	v_rcp_f32_e32 v179, v179
	v_rcp_f32_e32 v180, v180
	v_rcp_f32_e32 v181, v181
	v_mul_f32_e32 v98, v98, v178
	v_mul_f32_e32 v99, v99, v179
	v_mul_f32_e32 v100, v100, v180
	v_mul_f32_e32 v101, v101, v181
	v_cvt_pk_bf16_f32 v164, v110, v111
	v_cvt_pk_bf16_f32 v165, v112, v113
	v_cvt_pk_bf16_f32 v166, v106, v107
	v_cvt_pk_bf16_f32 v167, v108, v109
	v_cvt_pk_bf16_f32 v168, v102, v103
	v_cvt_pk_bf16_f32 v169, v104, v105
	v_cvt_pk_bf16_f32 v170, v98, v99
	v_cvt_pk_bf16_f32 v171, v100, v101
	ds_write_b64 v136, v[164:165]
	v_xor_b32_e32 v173, 0x20, v136
	ds_write_b64 v173, v[166:167]
	v_xor_b32_e32 v174, 0x40, v136
	ds_write_b64 v174, v[168:169]
	v_xor_b32_e32 v175, 0x60, v136
	ds_write_b64 v175, v[170:171]
	ds_read_b128 v[156:159], v135
	ds_read_b128 v[160:163], v135 offset:1024
	s_waitcnt lgkmcnt(6)
	buffer_store_dwordx4 v[148:151], v139, s[44:47], s11 offen
	s_add_u32 s11, s11, 0x18000
	buffer_store_dwordx4 v[152:155], v139, s[44:47], s11 offen
	s_add_u32 s11, s11, 0x18000
	v_mul_f32_e32 v177, v176, v226
	v_mul_f32_e32 v94, v177, v94
	v_mul_f32_e32 v95, v177, v95
	v_mul_f32_e32 v96, v177, v96
	v_mul_f32_e32 v97, v177, v97
	v_mul_f32_e32 v90, v177, v90
	v_mul_f32_e32 v91, v177, v91
	v_mul_f32_e32 v92, v177, v92
	v_mul_f32_e32 v93, v177, v93
	v_mul_f32_e32 v86, v177, v86
	v_mul_f32_e32 v87, v177, v87
	v_mul_f32_e32 v88, v177, v88
	v_mul_f32_e32 v89, v177, v89
	v_mul_f32_e32 v82, v177, v82
	v_mul_f32_e32 v83, v177, v83
	v_mul_f32_e32 v84, v177, v84
	v_mul_f32_e32 v85, v177, v85
	v_mul_f32_e32 v178, 0xbfb8aa3b, v94
	v_mul_f32_e32 v179, 0xbfb8aa3b, v95
	v_mul_f32_e32 v180, 0xbfb8aa3b, v96
	v_mul_f32_e32 v181, 0xbfb8aa3b, v97
	v_exp_f32_e32 v178, v178
	v_exp_f32_e32 v179, v179
	v_exp_f32_e32 v180, v180
	v_exp_f32_e32 v181, v181
	v_add_f32_e32 v178, 1.0, v178
	v_add_f32_e32 v179, 1.0, v179
	v_add_f32_e32 v180, 1.0, v180
	v_add_f32_e32 v181, 1.0, v181
	v_rcp_f32_e32 v178, v178
	v_rcp_f32_e32 v179, v179
	v_rcp_f32_e32 v180, v180
	v_rcp_f32_e32 v181, v181
	v_mul_f32_e32 v94, v94, v178
	v_mul_f32_e32 v95, v95, v179
	v_mul_f32_e32 v96, v96, v180
	v_mul_f32_e32 v97, v97, v181
	v_mul_f32_e32 v178, 0xbfb8aa3b, v90
	v_mul_f32_e32 v179, 0xbfb8aa3b, v91
	v_mul_f32_e32 v180, 0xbfb8aa3b, v92
	v_mul_f32_e32 v181, 0xbfb8aa3b, v93
	v_exp_f32_e32 v178, v178
	v_exp_f32_e32 v179, v179
	v_exp_f32_e32 v180, v180
	v_exp_f32_e32 v181, v181
	v_add_f32_e32 v178, 1.0, v178
	v_add_f32_e32 v179, 1.0, v179
	v_add_f32_e32 v180, 1.0, v180
	v_add_f32_e32 v181, 1.0, v181
	v_rcp_f32_e32 v178, v178
	v_rcp_f32_e32 v179, v179
	v_rcp_f32_e32 v180, v180
	v_rcp_f32_e32 v181, v181
	v_mul_f32_e32 v90, v90, v178
	v_mul_f32_e32 v91, v91, v179
	v_mul_f32_e32 v92, v92, v180
	v_mul_f32_e32 v93, v93, v181
	v_mul_f32_e32 v178, 0xbfb8aa3b, v86
	v_mul_f32_e32 v179, 0xbfb8aa3b, v87
	v_mul_f32_e32 v180, 0xbfb8aa3b, v88
	v_mul_f32_e32 v181, 0xbfb8aa3b, v89
	v_exp_f32_e32 v178, v178
	v_exp_f32_e32 v179, v179
	v_exp_f32_e32 v180, v180
	v_exp_f32_e32 v181, v181
	v_add_f32_e32 v178, 1.0, v178
	v_add_f32_e32 v179, 1.0, v179
	v_add_f32_e32 v180, 1.0, v180
	v_add_f32_e32 v181, 1.0, v181
	v_rcp_f32_e32 v178, v178
	v_rcp_f32_e32 v179, v179
	v_rcp_f32_e32 v180, v180
	v_rcp_f32_e32 v181, v181
	v_mul_f32_e32 v86, v86, v178
	v_mul_f32_e32 v87, v87, v179
	v_mul_f32_e32 v88, v88, v180
	v_mul_f32_e32 v89, v89, v181
	v_mul_f32_e32 v178, 0xbfb8aa3b, v82
	v_mul_f32_e32 v179, 0xbfb8aa3b, v83
	v_mul_f32_e32 v180, 0xbfb8aa3b, v84
	v_mul_f32_e32 v181, 0xbfb8aa3b, v85
	v_exp_f32_e32 v178, v178
	v_exp_f32_e32 v179, v179
	v_exp_f32_e32 v180, v180
	v_exp_f32_e32 v181, v181
	v_add_f32_e32 v178, 1.0, v178
	v_add_f32_e32 v179, 1.0, v179
	v_add_f32_e32 v180, 1.0, v180
	v_add_f32_e32 v181, 1.0, v181
	v_rcp_f32_e32 v178, v178
	v_rcp_f32_e32 v179, v179
	v_rcp_f32_e32 v180, v180
	v_rcp_f32_e32 v181, v181
	v_mul_f32_e32 v82, v82, v178
	v_mul_f32_e32 v83, v83, v179
	v_mul_f32_e32 v84, v84, v180
	v_mul_f32_e32 v85, v85, v181
	v_cvt_pk_bf16_f32 v140, v94, v95
	v_cvt_pk_bf16_f32 v141, v96, v97
	v_cvt_pk_bf16_f32 v142, v90, v91
	v_cvt_pk_bf16_f32 v143, v92, v93
	v_cvt_pk_bf16_f32 v144, v86, v87
	v_cvt_pk_bf16_f32 v145, v88, v89
	v_cvt_pk_bf16_f32 v146, v82, v83
	v_cvt_pk_bf16_f32 v147, v84, v85
	ds_write_b64 v136, v[140:141]
	v_xor_b32_e32 v173, 0x20, v136
	ds_write_b64 v173, v[142:143]
	v_xor_b32_e32 v174, 0x40, v136
	ds_write_b64 v174, v[144:145]
	v_xor_b32_e32 v175, 0x60, v136
	ds_write_b64 v175, v[146:147]
	ds_read_b128 v[148:151], v135
	ds_read_b128 v[152:155], v135 offset:1024
	s_waitcnt lgkmcnt(6)
	buffer_store_dwordx4 v[156:159], v139, s[44:47], s11 offen
	s_add_u32 s11, s11, 0x18000
	buffer_store_dwordx4 v[160:163], v139, s[44:47], s11 offen
	s_add_u32 s11, s11, 0x18000
	v_mul_f32_e32 v177, v176, v227
	v_mul_f32_e32 v78, v177, v78
	v_mul_f32_e32 v79, v177, v79
	v_mul_f32_e32 v80, v177, v80
	v_mul_f32_e32 v81, v177, v81
	v_mul_f32_e32 v74, v177, v74
	v_mul_f32_e32 v75, v177, v75
	v_mul_f32_e32 v76, v177, v76
	v_mul_f32_e32 v77, v177, v77
	v_mul_f32_e32 v70, v177, v70
	v_mul_f32_e32 v71, v177, v71
	v_mul_f32_e32 v72, v177, v72
	v_mul_f32_e32 v73, v177, v73
	v_mul_f32_e32 v66, v177, v66
	v_mul_f32_e32 v67, v177, v67
	v_mul_f32_e32 v68, v177, v68
	v_mul_f32_e32 v69, v177, v69
	v_mul_f32_e32 v178, 0xbfb8aa3b, v78
	v_mul_f32_e32 v179, 0xbfb8aa3b, v79
	v_mul_f32_e32 v180, 0xbfb8aa3b, v80
	v_mul_f32_e32 v181, 0xbfb8aa3b, v81
	v_exp_f32_e32 v178, v178
	v_exp_f32_e32 v179, v179
	v_exp_f32_e32 v180, v180
	v_exp_f32_e32 v181, v181
	v_add_f32_e32 v178, 1.0, v178
	v_add_f32_e32 v179, 1.0, v179
	v_add_f32_e32 v180, 1.0, v180
	v_add_f32_e32 v181, 1.0, v181
	v_rcp_f32_e32 v178, v178
	v_rcp_f32_e32 v179, v179
	v_rcp_f32_e32 v180, v180
	v_rcp_f32_e32 v181, v181
	v_mul_f32_e32 v78, v78, v178
	v_mul_f32_e32 v79, v79, v179
	v_mul_f32_e32 v80, v80, v180
	v_mul_f32_e32 v81, v81, v181
	v_mul_f32_e32 v178, 0xbfb8aa3b, v74
	v_mul_f32_e32 v179, 0xbfb8aa3b, v75
	v_mul_f32_e32 v180, 0xbfb8aa3b, v76
	v_mul_f32_e32 v181, 0xbfb8aa3b, v77
	v_exp_f32_e32 v178, v178
	v_exp_f32_e32 v179, v179
	v_exp_f32_e32 v180, v180
	v_exp_f32_e32 v181, v181
	v_add_f32_e32 v178, 1.0, v178
	v_add_f32_e32 v179, 1.0, v179
	v_add_f32_e32 v180, 1.0, v180
	v_add_f32_e32 v181, 1.0, v181
	v_rcp_f32_e32 v178, v178
	v_rcp_f32_e32 v179, v179
	v_rcp_f32_e32 v180, v180
	v_rcp_f32_e32 v181, v181
	v_mul_f32_e32 v74, v74, v178
	v_mul_f32_e32 v75, v75, v179
	v_mul_f32_e32 v76, v76, v180
	v_mul_f32_e32 v77, v77, v181
	v_mul_f32_e32 v178, 0xbfb8aa3b, v70
	v_mul_f32_e32 v179, 0xbfb8aa3b, v71
	v_mul_f32_e32 v180, 0xbfb8aa3b, v72
	v_mul_f32_e32 v181, 0xbfb8aa3b, v73
	v_exp_f32_e32 v178, v178
	v_exp_f32_e32 v179, v179
	v_exp_f32_e32 v180, v180
	v_exp_f32_e32 v181, v181
	v_add_f32_e32 v178, 1.0, v178
	v_add_f32_e32 v179, 1.0, v179
	v_add_f32_e32 v180, 1.0, v180
	v_add_f32_e32 v181, 1.0, v181
	v_rcp_f32_e32 v178, v178
	v_rcp_f32_e32 v179, v179
	v_rcp_f32_e32 v180, v180
	v_rcp_f32_e32 v181, v181
	v_mul_f32_e32 v70, v70, v178
	v_mul_f32_e32 v71, v71, v179
	v_mul_f32_e32 v72, v72, v180
	v_mul_f32_e32 v73, v73, v181
	v_mul_f32_e32 v178, 0xbfb8aa3b, v66
	v_mul_f32_e32 v179, 0xbfb8aa3b, v67
	v_mul_f32_e32 v180, 0xbfb8aa3b, v68
	v_mul_f32_e32 v181, 0xbfb8aa3b, v69
	v_exp_f32_e32 v178, v178
	v_exp_f32_e32 v179, v179
	v_exp_f32_e32 v180, v180
	v_exp_f32_e32 v181, v181
	v_add_f32_e32 v178, 1.0, v178
	v_add_f32_e32 v179, 1.0, v179
	v_add_f32_e32 v180, 1.0, v180
	v_add_f32_e32 v181, 1.0, v181
	v_rcp_f32_e32 v178, v178
	v_rcp_f32_e32 v179, v179
	v_rcp_f32_e32 v180, v180
	v_rcp_f32_e32 v181, v181
	v_mul_f32_e32 v66, v66, v178
	v_mul_f32_e32 v67, v67, v179
	v_mul_f32_e32 v68, v68, v180
	v_mul_f32_e32 v69, v69, v181
	v_cvt_pk_bf16_f32 v164, v78, v79
	v_cvt_pk_bf16_f32 v165, v80, v81
	v_cvt_pk_bf16_f32 v166, v74, v75
	v_cvt_pk_bf16_f32 v167, v76, v77
	v_cvt_pk_bf16_f32 v168, v70, v71
	v_cvt_pk_bf16_f32 v169, v72, v73
	v_cvt_pk_bf16_f32 v170, v66, v67
	v_cvt_pk_bf16_f32 v171, v68, v69
	ds_write_b64 v136, v[164:165]
	v_xor_b32_e32 v173, 0x20, v136
	ds_write_b64 v173, v[166:167]
	v_xor_b32_e32 v174, 0x40, v136
	ds_write_b64 v174, v[168:169]
	v_xor_b32_e32 v175, 0x60, v136
	ds_write_b64 v175, v[170:171]
	ds_read_b128 v[156:159], v135
	ds_read_b128 v[160:163], v135 offset:1024
	s_waitcnt lgkmcnt(6)
	buffer_store_dwordx4 v[148:151], v139, s[44:47], s11 offen
	s_add_u32 s11, s11, 0x18000
	buffer_store_dwordx4 v[152:155], v139, s[44:47], s11 offen
	s_add_u32 s11, s11, 0x18000
	v_mul_f32_e32 v177, v176, v228
	v_mul_f32_e32 v62, v177, v62
	v_mul_f32_e32 v63, v177, v63
	v_mul_f32_e32 v64, v177, v64
	v_mul_f32_e32 v65, v177, v65
	v_mul_f32_e32 v58, v177, v58
	v_mul_f32_e32 v59, v177, v59
	v_mul_f32_e32 v60, v177, v60
	v_mul_f32_e32 v61, v177, v61
	v_mul_f32_e32 v54, v177, v54
	v_mul_f32_e32 v55, v177, v55
	v_mul_f32_e32 v56, v177, v56
	v_mul_f32_e32 v57, v177, v57
	v_mul_f32_e32 v50, v177, v50
	v_mul_f32_e32 v51, v177, v51
	v_mul_f32_e32 v52, v177, v52
	v_mul_f32_e32 v53, v177, v53
	v_mul_f32_e32 v178, 0xbfb8aa3b, v62
	v_mul_f32_e32 v179, 0xbfb8aa3b, v63
	v_mul_f32_e32 v180, 0xbfb8aa3b, v64
	v_mul_f32_e32 v181, 0xbfb8aa3b, v65
	v_exp_f32_e32 v178, v178
	v_exp_f32_e32 v179, v179
	v_exp_f32_e32 v180, v180
	v_exp_f32_e32 v181, v181
	v_add_f32_e32 v178, 1.0, v178
	v_add_f32_e32 v179, 1.0, v179
	v_add_f32_e32 v180, 1.0, v180
	v_add_f32_e32 v181, 1.0, v181
	v_rcp_f32_e32 v178, v178
	v_rcp_f32_e32 v179, v179
	v_rcp_f32_e32 v180, v180
	v_rcp_f32_e32 v181, v181
	v_mul_f32_e32 v62, v62, v178
	v_mul_f32_e32 v63, v63, v179
	v_mul_f32_e32 v64, v64, v180
	v_mul_f32_e32 v65, v65, v181
	v_mul_f32_e32 v178, 0xbfb8aa3b, v58
	v_mul_f32_e32 v179, 0xbfb8aa3b, v59
	v_mul_f32_e32 v180, 0xbfb8aa3b, v60
	v_mul_f32_e32 v181, 0xbfb8aa3b, v61
	v_exp_f32_e32 v178, v178
	v_exp_f32_e32 v179, v179
	v_exp_f32_e32 v180, v180
	v_exp_f32_e32 v181, v181
	v_add_f32_e32 v178, 1.0, v178
	v_add_f32_e32 v179, 1.0, v179
	v_add_f32_e32 v180, 1.0, v180
	v_add_f32_e32 v181, 1.0, v181
	v_rcp_f32_e32 v178, v178
	v_rcp_f32_e32 v179, v179
	v_rcp_f32_e32 v180, v180
	v_rcp_f32_e32 v181, v181
	v_mul_f32_e32 v58, v58, v178
	v_mul_f32_e32 v59, v59, v179
	v_mul_f32_e32 v60, v60, v180
	v_mul_f32_e32 v61, v61, v181
	v_mul_f32_e32 v178, 0xbfb8aa3b, v54
	v_mul_f32_e32 v179, 0xbfb8aa3b, v55
	v_mul_f32_e32 v180, 0xbfb8aa3b, v56
	v_mul_f32_e32 v181, 0xbfb8aa3b, v57
	v_exp_f32_e32 v178, v178
	v_exp_f32_e32 v179, v179
	v_exp_f32_e32 v180, v180
	v_exp_f32_e32 v181, v181
	v_add_f32_e32 v178, 1.0, v178
	v_add_f32_e32 v179, 1.0, v179
	v_add_f32_e32 v180, 1.0, v180
	v_add_f32_e32 v181, 1.0, v181
	v_rcp_f32_e32 v178, v178
	v_rcp_f32_e32 v179, v179
	v_rcp_f32_e32 v180, v180
	v_rcp_f32_e32 v181, v181
	v_mul_f32_e32 v54, v54, v178
	v_mul_f32_e32 v55, v55, v179
	v_mul_f32_e32 v56, v56, v180
	v_mul_f32_e32 v57, v57, v181
	v_mul_f32_e32 v178, 0xbfb8aa3b, v50
	v_mul_f32_e32 v179, 0xbfb8aa3b, v51
	v_mul_f32_e32 v180, 0xbfb8aa3b, v52
	v_mul_f32_e32 v181, 0xbfb8aa3b, v53
	v_exp_f32_e32 v178, v178
	v_exp_f32_e32 v179, v179
	v_exp_f32_e32 v180, v180
	v_exp_f32_e32 v181, v181
	v_add_f32_e32 v178, 1.0, v178
	v_add_f32_e32 v179, 1.0, v179
	v_add_f32_e32 v180, 1.0, v180
	v_add_f32_e32 v181, 1.0, v181
	v_rcp_f32_e32 v178, v178
	v_rcp_f32_e32 v179, v179
	v_rcp_f32_e32 v180, v180
	v_rcp_f32_e32 v181, v181
	v_mul_f32_e32 v50, v50, v178
	v_mul_f32_e32 v51, v51, v179
	v_mul_f32_e32 v52, v52, v180
	v_mul_f32_e32 v53, v53, v181
	v_cvt_pk_bf16_f32 v140, v62, v63
	v_cvt_pk_bf16_f32 v141, v64, v65
	v_cvt_pk_bf16_f32 v142, v58, v59
	v_cvt_pk_bf16_f32 v143, v60, v61
	v_cvt_pk_bf16_f32 v144, v54, v55
	v_cvt_pk_bf16_f32 v145, v56, v57
	v_cvt_pk_bf16_f32 v146, v50, v51
	v_cvt_pk_bf16_f32 v147, v52, v53
	ds_write_b64 v136, v[140:141]
	v_xor_b32_e32 v173, 0x20, v136
	ds_write_b64 v173, v[142:143]
	v_xor_b32_e32 v174, 0x40, v136
	ds_write_b64 v174, v[144:145]
	v_xor_b32_e32 v175, 0x60, v136
	ds_write_b64 v175, v[146:147]
	ds_read_b128 v[148:151], v135
	ds_read_b128 v[152:155], v135 offset:1024
	s_waitcnt lgkmcnt(6)
	buffer_store_dwordx4 v[156:159], v139, s[44:47], s11 offen
	s_add_u32 s11, s11, 0x18000
	buffer_store_dwordx4 v[160:163], v139, s[44:47], s11 offen
	s_add_u32 s11, s11, 0x18000
	v_mul_f32_e32 v177, v176, v231
	v_mul_f32_e32 v46, v177, v46
	v_mul_f32_e32 v47, v177, v47
	v_mul_f32_e32 v48, v177, v48
	v_mul_f32_e32 v49, v177, v49
	v_mul_f32_e32 v42, v177, v42
	v_mul_f32_e32 v43, v177, v43
	v_mul_f32_e32 v44, v177, v44
	v_mul_f32_e32 v45, v177, v45
	v_mul_f32_e32 v38, v177, v38
	v_mul_f32_e32 v39, v177, v39
	v_mul_f32_e32 v40, v177, v40
	v_mul_f32_e32 v41, v177, v41
	v_mul_f32_e32 v34, v177, v34
	v_mul_f32_e32 v35, v177, v35
	v_mul_f32_e32 v36, v177, v36
	v_mul_f32_e32 v37, v177, v37
	v_mul_f32_e32 v178, 0xbfb8aa3b, v46
	v_mul_f32_e32 v179, 0xbfb8aa3b, v47
	v_mul_f32_e32 v180, 0xbfb8aa3b, v48
	v_mul_f32_e32 v181, 0xbfb8aa3b, v49
	v_exp_f32_e32 v178, v178
	v_exp_f32_e32 v179, v179
	v_exp_f32_e32 v180, v180
	v_exp_f32_e32 v181, v181
	v_add_f32_e32 v178, 1.0, v178
	v_add_f32_e32 v179, 1.0, v179
	v_add_f32_e32 v180, 1.0, v180
	v_add_f32_e32 v181, 1.0, v181
	v_rcp_f32_e32 v178, v178
	v_rcp_f32_e32 v179, v179
	v_rcp_f32_e32 v180, v180
	v_rcp_f32_e32 v181, v181
	v_mul_f32_e32 v46, v46, v178
	v_mul_f32_e32 v47, v47, v179
	v_mul_f32_e32 v48, v48, v180
	v_mul_f32_e32 v49, v49, v181
	v_mul_f32_e32 v178, 0xbfb8aa3b, v42
	v_mul_f32_e32 v179, 0xbfb8aa3b, v43
	v_mul_f32_e32 v180, 0xbfb8aa3b, v44
	v_mul_f32_e32 v181, 0xbfb8aa3b, v45
	v_exp_f32_e32 v178, v178
	v_exp_f32_e32 v179, v179
	v_exp_f32_e32 v180, v180
	v_exp_f32_e32 v181, v181
	v_add_f32_e32 v178, 1.0, v178
	v_add_f32_e32 v179, 1.0, v179
	v_add_f32_e32 v180, 1.0, v180
	v_add_f32_e32 v181, 1.0, v181
	v_rcp_f32_e32 v178, v178
	v_rcp_f32_e32 v179, v179
	v_rcp_f32_e32 v180, v180
	v_rcp_f32_e32 v181, v181
	v_mul_f32_e32 v42, v42, v178
	v_mul_f32_e32 v43, v43, v179
	v_mul_f32_e32 v44, v44, v180
	v_mul_f32_e32 v45, v45, v181
	v_mul_f32_e32 v178, 0xbfb8aa3b, v38
	v_mul_f32_e32 v179, 0xbfb8aa3b, v39
	v_mul_f32_e32 v180, 0xbfb8aa3b, v40
	v_mul_f32_e32 v181, 0xbfb8aa3b, v41
	v_exp_f32_e32 v178, v178
	v_exp_f32_e32 v179, v179
	v_exp_f32_e32 v180, v180
	v_exp_f32_e32 v181, v181
	v_add_f32_e32 v178, 1.0, v178
	v_add_f32_e32 v179, 1.0, v179
	v_add_f32_e32 v180, 1.0, v180
	v_add_f32_e32 v181, 1.0, v181
	v_rcp_f32_e32 v178, v178
	v_rcp_f32_e32 v179, v179
	v_rcp_f32_e32 v180, v180
	v_rcp_f32_e32 v181, v181
	v_mul_f32_e32 v38, v38, v178
	v_mul_f32_e32 v39, v39, v179
	v_mul_f32_e32 v40, v40, v180
	v_mul_f32_e32 v41, v41, v181
	v_mul_f32_e32 v178, 0xbfb8aa3b, v34
	v_mul_f32_e32 v179, 0xbfb8aa3b, v35
	v_mul_f32_e32 v180, 0xbfb8aa3b, v36
	v_mul_f32_e32 v181, 0xbfb8aa3b, v37
	v_exp_f32_e32 v178, v178
	v_exp_f32_e32 v179, v179
	v_exp_f32_e32 v180, v180
	v_exp_f32_e32 v181, v181
	v_add_f32_e32 v178, 1.0, v178
	v_add_f32_e32 v179, 1.0, v179
	v_add_f32_e32 v180, 1.0, v180
	v_add_f32_e32 v181, 1.0, v181
	v_rcp_f32_e32 v178, v178
	v_rcp_f32_e32 v179, v179
	v_rcp_f32_e32 v180, v180
	v_rcp_f32_e32 v181, v181
	v_mul_f32_e32 v34, v34, v178
	v_mul_f32_e32 v35, v35, v179
	v_mul_f32_e32 v36, v36, v180
	v_mul_f32_e32 v37, v37, v181
	v_cvt_pk_bf16_f32 v164, v46, v47
	v_cvt_pk_bf16_f32 v165, v48, v49
	v_cvt_pk_bf16_f32 v166, v42, v43
	v_cvt_pk_bf16_f32 v167, v44, v45
	v_cvt_pk_bf16_f32 v168, v38, v39
	v_cvt_pk_bf16_f32 v169, v40, v41
	v_cvt_pk_bf16_f32 v170, v34, v35
	v_cvt_pk_bf16_f32 v171, v36, v37
	ds_write_b64 v136, v[164:165]
	v_xor_b32_e32 v173, 0x20, v136
	ds_write_b64 v173, v[166:167]
	v_xor_b32_e32 v174, 0x40, v136
	ds_write_b64 v174, v[168:169]
	v_xor_b32_e32 v175, 0x60, v136
	ds_write_b64 v175, v[170:171]
	ds_read_b128 v[156:159], v135
	ds_read_b128 v[160:163], v135 offset:1024
	s_waitcnt lgkmcnt(6)
	buffer_store_dwordx4 v[148:151], v139, s[44:47], s11 offen
	s_add_u32 s11, s11, 0x18000
	buffer_store_dwordx4 v[152:155], v139, s[44:47], s11 offen
	s_add_u32 s11, s11, 0x18000
	v_mul_f32_e32 v177, v176, v254
	v_mul_f32_e32 v30, v177, v30
	v_mul_f32_e32 v31, v177, v31
	v_mul_f32_e32 v32, v177, v32
	v_mul_f32_e32 v33, v177, v33
	v_mul_f32_e32 v26, v177, v26
	v_mul_f32_e32 v27, v177, v27
	v_mul_f32_e32 v28, v177, v28
	v_mul_f32_e32 v29, v177, v29
	v_mul_f32_e32 v22, v177, v22
	v_mul_f32_e32 v23, v177, v23
	v_mul_f32_e32 v24, v177, v24
	v_mul_f32_e32 v25, v177, v25
	v_mul_f32_e32 v18, v177, v18
	v_mul_f32_e32 v19, v177, v19
	v_mul_f32_e32 v20, v177, v20
	v_mul_f32_e32 v21, v177, v21
	v_mul_f32_e32 v178, 0xbfb8aa3b, v30
	v_mul_f32_e32 v179, 0xbfb8aa3b, v31
	v_mul_f32_e32 v180, 0xbfb8aa3b, v32
	v_mul_f32_e32 v181, 0xbfb8aa3b, v33
	v_exp_f32_e32 v178, v178
	v_exp_f32_e32 v179, v179
	v_exp_f32_e32 v180, v180
	v_exp_f32_e32 v181, v181
	v_add_f32_e32 v178, 1.0, v178
	v_add_f32_e32 v179, 1.0, v179
	v_add_f32_e32 v180, 1.0, v180
	v_add_f32_e32 v181, 1.0, v181
	v_rcp_f32_e32 v178, v178
	v_rcp_f32_e32 v179, v179
	v_rcp_f32_e32 v180, v180
	v_rcp_f32_e32 v181, v181
	v_mul_f32_e32 v30, v30, v178
	v_mul_f32_e32 v31, v31, v179
	v_mul_f32_e32 v32, v32, v180
	v_mul_f32_e32 v33, v33, v181
	v_mul_f32_e32 v178, 0xbfb8aa3b, v26
	v_mul_f32_e32 v179, 0xbfb8aa3b, v27
	v_mul_f32_e32 v180, 0xbfb8aa3b, v28
	v_mul_f32_e32 v181, 0xbfb8aa3b, v29
	v_exp_f32_e32 v178, v178
	v_exp_f32_e32 v179, v179
	v_exp_f32_e32 v180, v180
	v_exp_f32_e32 v181, v181
	v_add_f32_e32 v178, 1.0, v178
	v_add_f32_e32 v179, 1.0, v179
	v_add_f32_e32 v180, 1.0, v180
	v_add_f32_e32 v181, 1.0, v181
	v_rcp_f32_e32 v178, v178
	v_rcp_f32_e32 v179, v179
	v_rcp_f32_e32 v180, v180
	v_rcp_f32_e32 v181, v181
	v_mul_f32_e32 v26, v26, v178
	v_mul_f32_e32 v27, v27, v179
	v_mul_f32_e32 v28, v28, v180
	v_mul_f32_e32 v29, v29, v181
	v_mul_f32_e32 v178, 0xbfb8aa3b, v22
	v_mul_f32_e32 v179, 0xbfb8aa3b, v23
	v_mul_f32_e32 v180, 0xbfb8aa3b, v24
	v_mul_f32_e32 v181, 0xbfb8aa3b, v25
	v_exp_f32_e32 v178, v178
	v_exp_f32_e32 v179, v179
	v_exp_f32_e32 v180, v180
	v_exp_f32_e32 v181, v181
	v_add_f32_e32 v178, 1.0, v178
	v_add_f32_e32 v179, 1.0, v179
	v_add_f32_e32 v180, 1.0, v180
	v_add_f32_e32 v181, 1.0, v181
	v_rcp_f32_e32 v178, v178
	v_rcp_f32_e32 v179, v179
	v_rcp_f32_e32 v180, v180
	v_rcp_f32_e32 v181, v181
	v_mul_f32_e32 v22, v22, v178
	v_mul_f32_e32 v23, v23, v179
	v_mul_f32_e32 v24, v24, v180
	v_mul_f32_e32 v25, v25, v181
	v_mul_f32_e32 v178, 0xbfb8aa3b, v18
	v_mul_f32_e32 v179, 0xbfb8aa3b, v19
	v_mul_f32_e32 v180, 0xbfb8aa3b, v20
	v_mul_f32_e32 v181, 0xbfb8aa3b, v21
	v_exp_f32_e32 v178, v178
	v_exp_f32_e32 v179, v179
	v_exp_f32_e32 v180, v180
	v_exp_f32_e32 v181, v181
	v_add_f32_e32 v178, 1.0, v178
	v_add_f32_e32 v179, 1.0, v179
	v_add_f32_e32 v180, 1.0, v180
	v_add_f32_e32 v181, 1.0, v181
	v_rcp_f32_e32 v178, v178
	v_rcp_f32_e32 v179, v179
	v_rcp_f32_e32 v180, v180
	v_rcp_f32_e32 v181, v181
	v_mul_f32_e32 v18, v18, v178
	v_mul_f32_e32 v19, v19, v179
	v_mul_f32_e32 v20, v20, v180
	v_mul_f32_e32 v21, v21, v181
	v_cvt_pk_bf16_f32 v140, v30, v31
	v_cvt_pk_bf16_f32 v141, v32, v33
	v_cvt_pk_bf16_f32 v142, v26, v27
	v_cvt_pk_bf16_f32 v143, v28, v29
	v_cvt_pk_bf16_f32 v144, v22, v23
	v_cvt_pk_bf16_f32 v145, v24, v25
	v_cvt_pk_bf16_f32 v146, v18, v19
	v_cvt_pk_bf16_f32 v147, v20, v21
	ds_write_b64 v136, v[140:141]
	v_xor_b32_e32 v173, 0x20, v136
	ds_write_b64 v173, v[142:143]
	v_xor_b32_e32 v174, 0x40, v136
	ds_write_b64 v174, v[144:145]
	v_xor_b32_e32 v175, 0x60, v136
	ds_write_b64 v175, v[146:147]
	ds_read_b128 v[148:151], v135
	ds_read_b128 v[152:155], v135 offset:1024
	s_waitcnt lgkmcnt(6)
	buffer_store_dwordx4 v[156:159], v139, s[44:47], s11 offen
	s_add_u32 s11, s11, 0x18000
	buffer_store_dwordx4 v[160:163], v139, s[44:47], s11 offen
	s_add_u32 s11, s11, 0x18000
	v_mul_f32_e32 v177, v176, v255
	v_mul_f32_e32 v14, v177, v14
	v_mul_f32_e32 v15, v177, v15
	v_mul_f32_e32 v16, v177, v16
	v_mul_f32_e32 v17, v177, v17
	v_mul_f32_e32 v10, v177, v10
	v_mul_f32_e32 v11, v177, v11
	v_mul_f32_e32 v12, v177, v12
	v_mul_f32_e32 v13, v177, v13
	v_mul_f32_e32 v6, v177, v6
	v_mul_f32_e32 v7, v177, v7
	v_mul_f32_e32 v8, v177, v8
	v_mul_f32_e32 v9, v177, v9
	v_mul_f32_e32 v2, v177, v2
	v_mul_f32_e32 v3, v177, v3
	v_mul_f32_e32 v4, v177, v4
	v_mul_f32_e32 v5, v177, v5
	v_mul_f32_e32 v178, 0xbfb8aa3b, v14
	v_mul_f32_e32 v179, 0xbfb8aa3b, v15
	v_mul_f32_e32 v180, 0xbfb8aa3b, v16
	v_mul_f32_e32 v181, 0xbfb8aa3b, v17
	v_exp_f32_e32 v178, v178
	v_exp_f32_e32 v179, v179
	v_exp_f32_e32 v180, v180
	v_exp_f32_e32 v181, v181
	v_add_f32_e32 v178, 1.0, v178
	v_add_f32_e32 v179, 1.0, v179
	v_add_f32_e32 v180, 1.0, v180
	v_add_f32_e32 v181, 1.0, v181
	v_rcp_f32_e32 v178, v178
	v_rcp_f32_e32 v179, v179
	v_rcp_f32_e32 v180, v180
	v_rcp_f32_e32 v181, v181
	v_mul_f32_e32 v14, v14, v178
	v_mul_f32_e32 v15, v15, v179
	v_mul_f32_e32 v16, v16, v180
	v_mul_f32_e32 v17, v17, v181
	v_mul_f32_e32 v178, 0xbfb8aa3b, v10
	v_mul_f32_e32 v179, 0xbfb8aa3b, v11
	v_mul_f32_e32 v180, 0xbfb8aa3b, v12
	v_mul_f32_e32 v181, 0xbfb8aa3b, v13
	v_exp_f32_e32 v178, v178
	v_exp_f32_e32 v179, v179
	v_exp_f32_e32 v180, v180
	v_exp_f32_e32 v181, v181
	v_add_f32_e32 v178, 1.0, v178
	v_add_f32_e32 v179, 1.0, v179
	v_add_f32_e32 v180, 1.0, v180
	v_add_f32_e32 v181, 1.0, v181
	v_rcp_f32_e32 v178, v178
	v_rcp_f32_e32 v179, v179
	v_rcp_f32_e32 v180, v180
	v_rcp_f32_e32 v181, v181
	v_mul_f32_e32 v10, v10, v178
	v_mul_f32_e32 v11, v11, v179
	v_mul_f32_e32 v12, v12, v180
	v_mul_f32_e32 v13, v13, v181
	v_mul_f32_e32 v178, 0xbfb8aa3b, v6
	v_mul_f32_e32 v179, 0xbfb8aa3b, v7
	v_mul_f32_e32 v180, 0xbfb8aa3b, v8
	v_mul_f32_e32 v181, 0xbfb8aa3b, v9
	v_exp_f32_e32 v178, v178
	v_exp_f32_e32 v179, v179
	v_exp_f32_e32 v180, v180
	v_exp_f32_e32 v181, v181
	v_add_f32_e32 v178, 1.0, v178
	v_add_f32_e32 v179, 1.0, v179
	v_add_f32_e32 v180, 1.0, v180
	v_add_f32_e32 v181, 1.0, v181
	v_rcp_f32_e32 v178, v178
	v_rcp_f32_e32 v179, v179
	v_rcp_f32_e32 v180, v180
	v_rcp_f32_e32 v181, v181
	v_mul_f32_e32 v6, v6, v178
	v_mul_f32_e32 v7, v7, v179
	v_mul_f32_e32 v8, v8, v180
	v_mul_f32_e32 v9, v9, v181
	v_mul_f32_e32 v178, 0xbfb8aa3b, v2
	v_mul_f32_e32 v179, 0xbfb8aa3b, v3
	v_mul_f32_e32 v180, 0xbfb8aa3b, v4
	v_mul_f32_e32 v181, 0xbfb8aa3b, v5
	v_exp_f32_e32 v178, v178
	v_exp_f32_e32 v179, v179
	v_exp_f32_e32 v180, v180
	v_exp_f32_e32 v181, v181
	v_add_f32_e32 v178, 1.0, v178
	v_add_f32_e32 v179, 1.0, v179
	v_add_f32_e32 v180, 1.0, v180
	v_add_f32_e32 v181, 1.0, v181
	v_rcp_f32_e32 v178, v178
	v_rcp_f32_e32 v179, v179
	v_rcp_f32_e32 v180, v180
	v_rcp_f32_e32 v181, v181
	v_mul_f32_e32 v2, v2, v178
	v_mul_f32_e32 v3, v3, v179
	v_mul_f32_e32 v4, v4, v180
	v_mul_f32_e32 v5, v5, v181
	v_cvt_pk_bf16_f32 v164, v14, v15
	v_cvt_pk_bf16_f32 v165, v16, v17
	v_cvt_pk_bf16_f32 v166, v10, v11
	v_cvt_pk_bf16_f32 v167, v12, v13
	v_cvt_pk_bf16_f32 v168, v6, v7
	v_cvt_pk_bf16_f32 v169, v8, v9
	v_cvt_pk_bf16_f32 v170, v2, v3
	v_cvt_pk_bf16_f32 v171, v4, v5
	ds_write_b64 v136, v[164:165]
	v_xor_b32_e32 v173, 0x20, v136
	ds_write_b64 v173, v[166:167]
	v_xor_b32_e32 v174, 0x40, v136
	ds_write_b64 v174, v[168:169]
	v_xor_b32_e32 v175, 0x60, v136
	ds_write_b64 v175, v[170:171]
	ds_read_b128 v[156:159], v135
	ds_read_b128 v[160:163], v135 offset:1024
	s_waitcnt lgkmcnt(6)
	buffer_store_dwordx4 v[148:151], v139, s[44:47], s11 offen
	s_add_u32 s11, s11, 0x18000
	buffer_store_dwordx4 v[152:155], v139, s[44:47], s11 offen
	s_add_u32 s11, s11, 0x18000
	s_waitcnt lgkmcnt(0)
	buffer_store_dwordx4 v[156:159], v139, s[44:47], s11 offen
	s_add_u32 s11, s11, 0x18000
	buffer_store_dwordx4 v[160:163], v139, s[44:47], s11 offen
	s_branch .LBB0_141
.Lp1_oldepi:
	s_ashr_i32 s2, s8, 2
	s_cmp_lt_u32 s8, 4
	s_cselect_b64 s[0:1], -1, 0
	s_lshl_b32 s4, s6, 8
	v_lshl_add_u32 v135, v212, 7, s4
	v_or_b32_e32 v130, v135, v1
	v_readlane_b32 s4, v230, 3
	v_ashrrev_i32_e32 v131, 31, v130
	v_readlane_b32 s5, v230, 4
	s_cmp_lt_i32 s2, 5
	v_readlane_b32 s6, v230, 5
	v_lshl_add_u64 v[132:133], v[130:131], 2, s[4:5]
	v_mov_b32_e32 v131, v224
	v_readlane_b32 s7, v230, 6
	s_cbranch_scc1 .LBB0_162
	s_cmp_eq_u32 s2, 5
	s_cselect_b64 s[4:5], -1, 0
	s_cbranch_execz .LBB0_163
	s_branch .LBB0_164

.LBB0_164:
	v_cndmask_b32_e64 v1, 1.0, v200, s[0:1]
	v_mul_f32_e32 v134, v1, v131
	v_pk_mul_f32 v[126:127], v[126:127], v[134:135] op_sel_hi:[1,0]
	s_andn2_b64 vcc, exec, s[4:5]
	v_pk_mul_f32 v[128:129], v[128:129], v[134:135] op_sel_hi:[1,0]
	s_cbranch_vccnz .LBB0_166
	v_mul_f32_e32 v131, 0xbfb8aa3b, v126
	v_exp_f32_e32 v131, v131
	s_nop 0
	v_add_f32_e32 v131, 1.0, v131
	v_rcp_f32_e32 v136, v131
	v_mul_f32_e32 v131, 0xbfb8aa3b, v127
	v_exp_f32_e32 v131, v131
	s_nop 0
	v_add_f32_e32 v131, 1.0, v131
	v_rcp_f32_e32 v137, v131
	v_mul_f32_e32 v131, 0xbfb8aa3b, v128
	v_exp_f32_e32 v131, v131
	v_pk_mul_f32 v[126:127], v[126:127], v[136:137]
	v_add_f32_e32 v131, 1.0, v131
	v_rcp_f32_e32 v136, v131
	v_mul_f32_e32 v131, 0xbfb8aa3b, v129
	v_exp_f32_e32 v131, v131
	s_nop 0
	v_add_f32_e32 v131, 1.0, v131
	v_rcp_f32_e32 v137, v131
	s_nop 0
	v_pk_mul_f32 v[128:129], v[128:129], v[136:137]

.LBB0_198:
	v_mov_b32_e32 v114, v225
	s_cmp_lt_i32 s2, 5
	s_cbranch_scc1 .LBB0_202

.LBB0_201:
	v_add_co_u32_e32 v116, vcc, 0xc0000, v138
	s_nop 1
	v_addc_co_u32_e32 v117, vcc, 0, v139, vcc
	global_store_dwordx2 v[116:117], v[114:115], off
	v_mov_b32_e32 v114, v225
	s_cmp_lt_i32 s2, 5
	s_cbranch_scc0 .LBB0_199

.LBB0_204:
	v_mul_f32_e32 v114, v1, v114
	v_pk_mul_f32 v[116:117], v[110:111], v[114:115] op_sel_hi:[1,0]
	s_andn2_b64 vcc, exec, s[6:7]
	v_pk_mul_f32 v[118:119], v[112:113], v[114:115] op_sel_hi:[1,0]
	s_cbranch_vccnz .LBB0_206
	v_mul_f32_e32 v110, 0xbfb8aa3b, v116
	v_mul_f32_e32 v111, 0xbfb8aa3b, v117
	v_exp_f32_e32 v110, v110
	v_exp_f32_e32 v111, v111
	v_add_f32_e32 v110, 1.0, v110
	v_add_f32_e32 v111, 1.0, v111
	v_rcp_f32_e32 v110, v110
	v_rcp_f32_e32 v111, v111
	s_nop 0
	v_pk_mul_f32 v[116:117], v[116:117], v[110:111]
	v_mul_f32_e32 v110, 0xbfb8aa3b, v118
	v_mul_f32_e32 v111, 0xbfb8aa3b, v119
	v_exp_f32_e32 v110, v110
	v_exp_f32_e32 v111, v111
	v_add_f32_e32 v110, 1.0, v110
	v_add_f32_e32 v111, 1.0, v111
	v_rcp_f32_e32 v110, v110
	v_rcp_f32_e32 v111, v111
	s_nop 0
	v_pk_mul_f32 v[118:119], v[118:119], v[110:111]

.LBB0_238:
	v_mov_b32_e32 v98, v226
	s_cmp_lt_i32 s2, 5
	s_cbranch_scc1 .LBB0_242

.LBB0_241:
	v_add_co_u32_e32 v100, vcc, 0xc0000, v116
	s_nop 1
	v_addc_co_u32_e32 v101, vcc, 0, v117, vcc
	global_store_dwordx2 v[100:101], v[98:99], off
	v_mov_b32_e32 v98, v226
	s_cmp_lt_i32 s2, 5
	s_cbranch_scc0 .LBB0_239

.LBB0_244:
	v_mul_f32_e32 v98, v1, v98
	v_pk_mul_f32 v[102:103], v[94:95], v[98:99] op_sel_hi:[1,0]
	s_andn2_b64 vcc, exec, s[6:7]
	v_pk_mul_f32 v[100:101], v[96:97], v[98:99] op_sel_hi:[1,0]
	s_cbranch_vccnz .LBB0_246
	v_mul_f32_e32 v94, 0xbfb8aa3b, v102
	v_mul_f32_e32 v95, 0xbfb8aa3b, v103
	v_exp_f32_e32 v94, v94
	v_exp_f32_e32 v95, v95
	v_add_f32_e32 v94, 1.0, v94
	v_add_f32_e32 v95, 1.0, v95
	v_rcp_f32_e32 v94, v94
	v_rcp_f32_e32 v95, v95
	s_nop 0
	v_pk_mul_f32 v[102:103], v[102:103], v[94:95]
	v_mul_f32_e32 v94, 0xbfb8aa3b, v100
	v_mul_f32_e32 v95, 0xbfb8aa3b, v101
	v_exp_f32_e32 v94, v94
	v_exp_f32_e32 v95, v95
	v_add_f32_e32 v94, 1.0, v94
	v_add_f32_e32 v95, 1.0, v95
	v_rcp_f32_e32 v94, v94
	v_rcp_f32_e32 v95, v95
	s_nop 0
	v_pk_mul_f32 v[100:101], v[100:101], v[94:95]

.LBB0_278:
	v_mov_b32_e32 v82, v227
	s_cmp_lt_i32 s2, 5
	s_cbranch_scc1 .LBB0_282

.LBB0_281:
	v_add_co_u32_e32 v84, vcc, 0xc0000, v96
	s_nop 1
	v_addc_co_u32_e32 v85, vcc, 0, v97, vcc
	global_store_dwordx2 v[84:85], v[82:83], off
	v_mov_b32_e32 v82, v227
	s_cmp_lt_i32 s2, 5
	s_cbranch_scc0 .LBB0_279

.LBB0_284:
	v_mul_f32_e32 v82, v1, v82
	v_pk_mul_f32 v[86:87], v[78:79], v[82:83] op_sel_hi:[1,0]
	s_andn2_b64 vcc, exec, s[6:7]
	v_pk_mul_f32 v[84:85], v[80:81], v[82:83] op_sel_hi:[1,0]
	s_cbranch_vccnz .LBB0_286
	v_mul_f32_e32 v78, 0xbfb8aa3b, v86
	v_mul_f32_e32 v79, 0xbfb8aa3b, v87
	v_exp_f32_e32 v78, v78
	v_exp_f32_e32 v79, v79
	v_add_f32_e32 v78, 1.0, v78
	v_add_f32_e32 v79, 1.0, v79
	v_rcp_f32_e32 v78, v78
	v_rcp_f32_e32 v79, v79
	s_nop 0
	v_pk_mul_f32 v[86:87], v[86:87], v[78:79]
	v_mul_f32_e32 v78, 0xbfb8aa3b, v84
	v_mul_f32_e32 v79, 0xbfb8aa3b, v85
	v_exp_f32_e32 v78, v78
	v_exp_f32_e32 v79, v79
	v_add_f32_e32 v78, 1.0, v78
	v_add_f32_e32 v79, 1.0, v79
	v_rcp_f32_e32 v78, v78
	v_rcp_f32_e32 v79, v79
	s_nop 0
	v_pk_mul_f32 v[84:85], v[84:85], v[78:79]

.LBB0_318:
	v_mov_b32_e32 v66, v228
	s_cmp_lt_i32 s2, 5
	s_cbranch_scc1 .LBB0_322

.LBB0_321:
	v_add_co_u32_e32 v68, vcc, 0xc0000, v80
	s_nop 1
	v_addc_co_u32_e32 v69, vcc, 0, v81, vcc
	global_store_dwordx2 v[68:69], v[66:67], off
	v_mov_b32_e32 v66, v228
	s_cmp_lt_i32 s2, 5
	s_cbranch_scc0 .LBB0_319

.LBB0_324:
	v_mul_f32_e32 v66, v1, v66
	v_pk_mul_f32 v[70:71], v[62:63], v[66:67] op_sel_hi:[1,0]
	s_andn2_b64 vcc, exec, s[6:7]
	v_pk_mul_f32 v[68:69], v[64:65], v[66:67] op_sel_hi:[1,0]
	s_cbranch_vccnz .LBB0_326
	v_mul_f32_e32 v62, 0xbfb8aa3b, v70
	v_mul_f32_e32 v63, 0xbfb8aa3b, v71
	v_exp_f32_e32 v62, v62
	v_exp_f32_e32 v63, v63
	v_add_f32_e32 v62, 1.0, v62
	v_add_f32_e32 v63, 1.0, v63
	v_rcp_f32_e32 v62, v62
	v_rcp_f32_e32 v63, v63
	s_nop 0
	v_pk_mul_f32 v[70:71], v[70:71], v[62:63]
	v_mul_f32_e32 v62, 0xbfb8aa3b, v68
	v_mul_f32_e32 v63, 0xbfb8aa3b, v69
	v_exp_f32_e32 v62, v62
	v_exp_f32_e32 v63, v63
	v_add_f32_e32 v62, 1.0, v62
	v_add_f32_e32 v63, 1.0, v63
	v_rcp_f32_e32 v62, v62
	v_rcp_f32_e32 v63, v63
	s_nop 0
	v_pk_mul_f32 v[68:69], v[68:69], v[62:63]

.LBB0_358:
	v_mov_b32_e32 v50, v231
	s_cmp_lt_i32 s2, 5
	s_cbranch_scc1 .LBB0_362

.LBB0_361:
	v_add_co_u32_e32 v52, vcc, 0xc0000, v64
	s_nop 1
	v_addc_co_u32_e32 v53, vcc, 0, v65, vcc
	global_store_dwordx2 v[52:53], v[50:51], off
	v_mov_b32_e32 v50, v231
	s_cmp_lt_i32 s2, 5
	s_cbranch_scc0 .LBB0_359

.LBB0_364:
	v_mul_f32_e32 v50, v1, v50
	v_pk_mul_f32 v[54:55], v[46:47], v[50:51] op_sel_hi:[1,0]
	s_andn2_b64 vcc, exec, s[6:7]
	v_pk_mul_f32 v[52:53], v[48:49], v[50:51] op_sel_hi:[1,0]
	s_cbranch_vccnz .LBB0_366
	v_mul_f32_e32 v46, 0xbfb8aa3b, v54
	v_mul_f32_e32 v47, 0xbfb8aa3b, v55
	v_exp_f32_e32 v46, v46
	v_exp_f32_e32 v47, v47
	v_add_f32_e32 v46, 1.0, v46
	v_add_f32_e32 v47, 1.0, v47
	v_rcp_f32_e32 v46, v46
	v_rcp_f32_e32 v47, v47
	s_nop 0
	v_pk_mul_f32 v[54:55], v[54:55], v[46:47]
	v_mul_f32_e32 v46, 0xbfb8aa3b, v52
	v_mul_f32_e32 v47, 0xbfb8aa3b, v53
	v_exp_f32_e32 v46, v46
	v_exp_f32_e32 v47, v47
	v_add_f32_e32 v46, 1.0, v46
	v_add_f32_e32 v47, 1.0, v47
	v_rcp_f32_e32 v46, v46
	v_rcp_f32_e32 v47, v47
	s_nop 0
	v_pk_mul_f32 v[52:53], v[52:53], v[46:47]

.LBB0_398:
	v_mov_b32_e32 v34, v254
	s_cmp_lt_i32 s2, 5
	s_cbranch_scc1 .LBB0_402

.LBB0_401:
	v_add_co_u32_e32 v36, vcc, 0xc0000, v48
	s_nop 1
	v_addc_co_u32_e32 v37, vcc, 0, v49, vcc
	global_store_dwordx2 v[36:37], v[34:35], off
	v_mov_b32_e32 v34, v254
	s_cmp_lt_i32 s2, 5
	s_cbranch_scc0 .LBB0_399

.LBB0_404:
	v_mul_f32_e32 v34, v1, v34
	v_pk_mul_f32 v[38:39], v[30:31], v[34:35] op_sel_hi:[1,0]
	s_andn2_b64 vcc, exec, s[6:7]
	v_pk_mul_f32 v[36:37], v[32:33], v[34:35] op_sel_hi:[1,0]
	s_cbranch_vccnz .LBB0_406
	v_mul_f32_e32 v30, 0xbfb8aa3b, v38
	v_mul_f32_e32 v31, 0xbfb8aa3b, v39
	v_exp_f32_e32 v30, v30
	v_exp_f32_e32 v31, v31
	v_add_f32_e32 v30, 1.0, v30
	v_add_f32_e32 v31, 1.0, v31
	v_rcp_f32_e32 v30, v30
	v_rcp_f32_e32 v31, v31
	s_nop 0
	v_pk_mul_f32 v[38:39], v[38:39], v[30:31]
	v_mul_f32_e32 v30, 0xbfb8aa3b, v36
	v_mul_f32_e32 v31, 0xbfb8aa3b, v37
	v_exp_f32_e32 v30, v30
	v_exp_f32_e32 v31, v31
	v_add_f32_e32 v30, 1.0, v30
	v_add_f32_e32 v31, 1.0, v31
	v_rcp_f32_e32 v30, v30
	v_rcp_f32_e32 v31, v31
	s_nop 0
	v_pk_mul_f32 v[36:37], v[36:37], v[30:31]

.LBB0_438:
	v_mov_b32_e32 v18, v255
	s_cmp_lt_i32 s2, 5
	s_cbranch_scc1 .LBB0_442

.LBB0_441:
	v_add_co_u32_e32 v20, vcc, 0xc0000, v32
	s_nop 1
	v_addc_co_u32_e32 v21, vcc, 0, v33, vcc
	global_store_dwordx2 v[20:21], v[18:19], off
	v_mov_b32_e32 v18, v255
	s_cmp_lt_i32 s2, 5
	s_cbranch_scc0 .LBB0_439

.LBB0_444:
	v_mul_f32_e32 v18, v1, v18
	v_pk_mul_f32 v[22:23], v[14:15], v[18:19] op_sel_hi:[1,0]
	s_andn2_b64 vcc, exec, s[6:7]
	v_pk_mul_f32 v[20:21], v[16:17], v[18:19] op_sel_hi:[1,0]
	s_cbranch_vccnz .LBB0_446
	v_mul_f32_e32 v1, 0xbfb8aa3b, v22
	v_exp_f32_e32 v1, v1
	s_nop 0
	v_add_f32_e32 v1, 1.0, v1
	v_rcp_f32_e32 v14, v1
	v_mul_f32_e32 v1, 0xbfb8aa3b, v23
	v_exp_f32_e32 v1, v1
	s_nop 0
	v_add_f32_e32 v1, 1.0, v1
	v_rcp_f32_e32 v15, v1
	v_mul_f32_e32 v1, 0xbfb8aa3b, v20
	v_exp_f32_e32 v1, v1
	v_pk_mul_f32 v[22:23], v[22:23], v[14:15]
	v_add_f32_e32 v1, 1.0, v1
	v_rcp_f32_e32 v14, v1
	v_mul_f32_e32 v1, 0xbfb8aa3b, v21
	v_exp_f32_e32 v1, v1
	s_nop 0
	v_add_f32_e32 v1, 1.0, v1
	v_rcp_f32_e32 v15, v1
	s_nop 0
	v_pk_mul_f32 v[20:21], v[20:21], v[14:15]

	.amdhsa_kernel _Z4mega6Params
		.amdhsa_group_segment_fixed_size 148752
		.amdhsa_private_segment_fixed_size 0
		.amdhsa_kernarg_size 584
		.amdhsa_user_sgpr_count 2
		.amdhsa_user_sgpr_dispatch_ptr 0
		.amdhsa_user_sgpr_queue_ptr 0
		.amdhsa_user_sgpr_kernarg_segment_ptr 1
		.amdhsa_user_sgpr_dispatch_id 0
		.amdhsa_user_sgpr_kernarg_preload_length 0
		.amdhsa_user_sgpr_kernarg_preload_offset 0
		.amdhsa_user_sgpr_private_segment_size 0
		.amdhsa_uses_dynamic_stack 0
		.amdhsa_enable_private_segment 0
		.amdhsa_system_sgpr_workgroup_id_x 1
		.amdhsa_system_sgpr_workgroup_id_y 0
		.amdhsa_system_sgpr_workgroup_id_z 0
		.amdhsa_system_sgpr_workgroup_info 0
		.amdhsa_system_vgpr_workitem_id 2
		.amdhsa_next_free_vgpr 256
		.amdhsa_next_free_sgpr 100
		.amdhsa_accum_offset 256
		.amdhsa_reserve_vcc 1
		.amdhsa_float_round_mode_32 0
		.amdhsa_float_round_mode_16_64 0
		.amdhsa_float_denorm_mode_32 3
		.amdhsa_float_denorm_mode_16_64 3
		.amdhsa_dx10_clamp 1
		.amdhsa_ieee_mode 1
		.amdhsa_fp16_overflow 0
		.amdhsa_tg_split 0
		.amdhsa_exception_fp_ieee_invalid_op 0
		.amdhsa_exception_fp_denorm_src 0
		.amdhsa_exception_fp_ieee_div_zero 0
		.amdhsa_exception_fp_ieee_overflow 0
		.amdhsa_exception_fp_ieee_underflow 0
		.amdhsa_exception_fp_ieee_inexact 0
		.amdhsa_exception_int_div_zero 0
	.end_amdhsa_kernel

amdhsa.kernels:
  - .agpr_count:     0
    .args:
      - .offset:         0
        .size:           328
        .value_kind:     by_value
      - .offset:         328
        .size:           4
        .value_kind:     hidden_block_count_x
      - .offset:         332
        .size:           4
        .value_kind:     hidden_block_count_y
      - .offset:         336
        .size:           4
        .value_kind:     hidden_block_count_z
      - .offset:         340
        .size:           2
        .value_kind:     hidden_group_size_x
      - .offset:         342
        .size:           2
        .value_kind:     hidden_group_size_y
      - .offset:         344
        .size:           2
        .value_kind:     hidden_group_size_z
      - .offset:         346
        .size:           2
        .value_kind:     hidden_remainder_x
      - .offset:         348
        .size:           2
        .value_kind:     hidden_remainder_y
      - .offset:         350
        .size:           2
        .value_kind:     hidden_remainder_z
      - .offset:         368
        .size:           8
        .value_kind:     hidden_global_offset_x
      - .offset:         376
        .size:           8
        .value_kind:     hidden_global_offset_y
      - .offset:         384
        .size:           8
        .value_kind:     hidden_global_offset_z
      - .offset:         392
        .size:           2
        .value_kind:     hidden_grid_dims
      - .offset:         416
        .size:           8
        .value_kind:     hidden_multigrid_sync_arg
    .group_segment_fixed_size: 148752
    .kernarg_segment_align: 8
    .kernarg_segment_size: 584
    .language:       OpenCL C
    .language_version:
      - 2
      - 0
    .max_flat_workgroup_size: 512
    .name:           _Z4mega6Params
    .private_segment_fixed_size: 0
    .sgpr_count:     106
    .sgpr_spill_count: 124
    .symbol:         _Z4mega6Params.kd
    .uniform_work_group_size: 1
    .uses_dynamic_stack: false
    .vgpr_count:     256
    .vgpr_spill_count: 0
    .wavefront_size: 64
